# speedup vs baseline: 1.0062x; 1.0062x over previous
;     __device__ __forceinline__ void operator()(const f32x4 (&acc)[2][2][4][2], const Unit& u, int wr, int wc, int fr, int fq) const {
;     ...
;         unsigned long long sq[2][4];
; #pragma unroll
;         for (int ai = 0; ai < 2; ++ai)
; #pragma unroll
;             for (int m = 0; m < 4; ++m) sq[ai][m] = ssq[row0 + ai * HALF + m * 16];
;         const float* gg = (t == 0) ? qg : kg; const float osc = (t == 0) ? scale0 : 1.0f;
;         f32x4 g[2][2];
; #pragma unroll
;         for (int bj = 0; bj < 2; ++bj)
; #pragma unroll
;             for (int n = 0; n < 2; ++n) g[bj][n] = *(const f32x4*)(gg + 32 * bj + 8 * fq + 4 * n) * osc;
;         const int col0 = (u.pn & 3) * BM + wc * 64 + 8 * fq;
;         const float sgn = (fq == 0) ? -1.0f : 1.0f; const bool rot = fq < 2;
; #pragma unroll
;         for (int ai = 0; ai < 2; ++ai)
; #pragma unroll
;             for (int m = 0; m < 4; ++m) { const int row = row0 + ai * HALF + m * 16;
;                 f32x4 v[2][2]; float ss = 0.f;
; #pragma unroll
;                 for (int bj = 0; bj < 2; ++bj)
; #pragma unroll
;                     for (int n = 0; n < 2; ++n) { v[bj][n] = acc[ai][bj][m][n]; ss += (v[bj][n][0] * v[bj][n][0] + v[bj][n][1] * v[bj][n][1]) + (v[bj][n][2] * v[bj][n][2] + v[bj][n][3] * v[bj][n][3]); }
;                 ss += __shfl_xor(ss, 16); ss += __shfl_xor(ss, 32);
;                 const float rs = __builtin_amdgcn_rsqf((float)sq[ai][m] * (1.0f / (1024.0f * 1048576.0f)) + RMS_EPS);
;                 const float rn = rs * __builtin_amdgcn_rsqf(rs * rs * ss * (1.0f / 64.0f) + RMS_EPS);
; #pragma unroll
;                 for (int bj = 0; bj < 2; ++bj)
; #pragma unroll
;                     for (int n = 0; n < 2; ++n) v[bj][n] = v[bj][n] * rn * g[bj][n];
;                 const f32x4 c0 = *(const f32x4*)(cs + (size_t)row * 8), c1 = *(const f32x4*)(cs + (size_t)row * 8 + 4), s0 = *(const f32x4*)(sn + (size_t)row * 8), s1 = *(const f32x4*)(sn + (size_t)row * 8 + 4);
.LBB0_137:
	s_ashr_i32 s26, s47, 2
	s_ashr_i32 s27, s26, 31
	v_lshl_add_u32 v148, s22, 8, v182
	s_lshl_b64 s[22:23], s[26:27], 26
	s_add_u32 s22, s56, s22
	s_addc_u32 s23, s57, s23
	v_or_b32_e32 v146, 16, v148
	v_or_b32_e32 v144, 32, v148
	v_or_b32_e32 v142, 48, v148
	s_mov_b64 s[24:25], -1
	s_cmp_lg_u32 s26, 2
	v_ashrrev_i32_e32 v149, 31, v148
	v_ashrrev_i32_e32 v147, 31, v146
	v_ashrrev_i32_e32 v145, 31, v144
	v_ashrrev_i32_e32 v143, 31, v142
	s_cbranch_scc0 .LBB0_140
	v_readlane_b32 s24, v255, 21
	v_readlane_b32 s25, v255, 22
	s_cmp_lt_u32 s47, 4
	s_cselect_b64 vcc, -1, 0
	v_lshl_add_u64 v[150:151], v[148:149], 3, s[24:25]
	global_load_dwordx2 v[158:159], v[150:151], off
	v_readlane_b32 s72, v254, 50
	s_and_b64 s[24:25], vcc, exec
	v_readlane_b32 s74, v254, 52
	v_readlane_b32 s73, v254, 51
	v_readlane_b32 s75, v254, 53
	s_cselect_b32 s17, s72, s74
	s_cselect_b32 s15, s73, s75
	s_add_u32 s24, s17, s12
	s_addc_u32 s25, s15, s13
	global_load_dwordx4 v[154:157], v187, s[24:25]
	global_load_dwordx4 v[166:169], v187, s[24:25] offset:16
	global_load_dwordx4 v[190:193], v187, s[24:25] offset:128
	global_load_dwordx4 v[194:197], v187, s[24:25] offset:144
	v_readlane_b32 s24, v254, 11
	v_readlane_b32 s26, v254, 13
	v_lshlrev_b64 v[152:153], 5, v[148:149]
	v_readlane_b32 s25, v254, 12
	v_readlane_b32 s27, v254, 14
	global_load_dwordx2 v[180:181], v[150:151], off offset:128
	global_load_dwordx2 v[178:179], v[150:151], off offset:256
	global_load_dwordx2 v[176:177], v[150:151], off offset:384
	v_lshl_add_u64 v[170:171], s[24:25], 0, v[152:153]
	v_lshl_add_u64 v[152:153], s[26:27], 0, v[152:153]
	global_load_dwordx4 v[198:201], v[170:171], off offset:16
	global_load_dwordx4 v[202:205], v[170:171], off
	global_load_dwordx4 v[206:209], v[152:153], off offset:16
	global_load_dwordx4 v[218:221], v[152:153], off
	global_load_dwordx2 v[174:175], v[150:151], off offset:1024
	global_load_dwordx2 v[172:173], v[150:151], off offset:1152
	s_nop 0
	global_load_dwordx2 v[170:171], v[150:151], off offset:1280
	global_load_dwordx2 v[152:153], v[150:151], off offset:1408
	v_pk_mul_f32 v[160:161], v[128:129], v[128:129]
	v_pk_mul_f32 v[162:163], v[126:127], v[126:127]
	v_pk_mul_f32 v[164:165], v[124:125], v[124:125]
	v_pk_mul_f32 v[188:189], v[122:123], v[122:123]
	v_pk_mov_b32 v[150:151], v[162:163], v[160:161] op_sel:[1,0]
	v_mov_b32_e32 v163, v161
	v_pk_mov_b32 v[160:161], v[188:189], v[164:165] op_sel:[1,0]
	v_mov_b32_e32 v189, v165
	v_and_b32_e32 v213, 64, v243
	v_mul_f32_e32 v0, v119, v119
	v_mul_f32_e32 v212, v121, v121
	v_pk_add_f32 v[150:151], v[150:151], v[162:163]
	v_pk_add_f32 v[160:161], v[160:161], v[188:189]
	v_mul_f32_e32 v215, v114, v114
	v_mul_f32_e32 v216, v115, v115
	v_mul_f32_e32 v217, v116, v116
	v_mul_f32_e32 v222, v117, v117
	v_add_u32_e32 v223, 64, v213
	v_pk_fma_f32 v[164:165], v[118:119], v[118:119], v[0:1] op_sel_hi:[1,1,0]
	v_pk_fma_f32 v[212:213], v[120:121], v[120:121], v[212:213] op_sel_hi:[1,1,0]
	v_pk_add_f32 v[150:151], v[150:151], v[150:151] op_sel:[0,1] op_sel_hi:[1,0]
	v_pk_add_f32 v[160:161], v[160:161], v[160:161] op_sel:[0,1] op_sel_hi:[1,0]
	v_xor_b32_e32 v211, 16, v243
	v_mov_b32_e32 v165, v217
	v_mov_b32_e32 v213, v222
	v_mov_b32_e32 v151, v215
	v_mov_b32_e32 v161, v216
	v_cndmask_b32_e32 v210, 1.0, v231, vcc
	v_cmp_lt_i32_e32 vcc, v211, v223
	v_pk_add_f32 v[162:163], v[164:165], v[212:213]
	v_pk_add_f32 v[150:151], v[150:151], v[160:161]
	v_cndmask_b32_e32 v0, v243, v211, vcc
	v_pk_add_f32 v[150:151], v[150:151], v[162:163]
	v_lshlrev_b32_e32 v188, 2, v0
	v_add_f32_e32 v0, v150, v151
	ds_bpermute_b32 v150, v188, v0
	v_xor_b32_e32 v214, 32, v243
	v_cmp_lt_i32_e32 vcc, v214, v223
	s_lshl_b32 s15, s47, 8
	s_and_b32 s15, s15, 0x300
	v_cndmask_b32_e32 v151, v243, v214, vcc
	v_lshlrev_b32_e32 v189, 2, v151
	s_waitcnt lgkmcnt(0)
	v_add_f32_e32 v160, v0, v150
	v_mov_b32_e32 v161, v160
	s_nop 1
	v_permlane32_swap_b32_e32 v161, v160
	v_or_b32_e32 v0, s15, v184
	v_lshlrev_b32_e32 v0, 1, v0
	v_lshl_add_u64 v[150:151], s[22:23], 0, v[0:1]
	v_readlane_b32 s76, v254, 54
	s_waitcnt lgkmcnt(0)
	v_add_f32_e32 v0, v160, v161
	v_readlane_b32 s77, v254, 55
	v_readlane_b32 s78, v254, 56
	v_readlane_b32 s79, v254, 57
	s_waitcnt vmcnt(0)
	v_ffbh_u32_e32 v160, v159
	v_min_u32_e32 v160, 32, v160
	v_lshlrev_b64 v[158:159], v160, v[158:159]
	v_min_u32_e32 v158, 1, v158
	v_or_b32_e32 v158, v159, v158
	v_cvt_f32_u32_e32 v158, v158
	v_sub_u32_e32 v159, 32, v160
	v_pk_mul_f32 v[162:163], v[210:211], v[154:155] op_sel_hi:[0,1]
	v_ldexp_f32 v154, v158, v159
	v_fmamk_f32 v154, v154, 0x30800000, v240
	v_pk_mul_f32 v[160:161], v[210:211], v[156:157] op_sel_hi:[0,1]
	v_rsq_f32_e32 v211, v154
	v_mov_b32_e32 v225, v202
	v_mul_f32_e32 v156, v211, v211
	v_mul_f32_e32 v0, v156, v0
	v_fmamk_f32 v0, v0, 0x3c800000, v240
	v_rsq_f32_e32 v0, v0
	v_pk_mul_f32 v[164:165], v[210:211], v[168:169] op_sel_hi:[0,1]
	v_pk_mul_f32 v[168:169], v[210:211], v[190:191] op_sel_hi:[0,1]
	v_pk_mul_f32 v[166:167], v[210:211], v[166:167] op_sel_hi:[0,1]
	v_mul_f32_e32 v0, v211, v0
	v_pk_mul_f32 v[190:191], v[126:127], v[0:1] op_sel_hi:[1,0]
	v_pk_mul_f32 v[154:155], v[210:211], v[192:193] op_sel_hi:[0,1]
	v_pk_mul_f32 v[190:191], v[162:163], v[190:191]
	ds_bpermute_b32 v222, v188, v190
	v_pk_mul_f32 v[156:157], v[210:211], v[196:197] op_sel_hi:[0,1]
	v_pk_mul_f32 v[158:159], v[210:211], v[194:195] op_sel_hi:[0,1]
	v_pk_mul_f32 v[192:193], v[128:129], v[0:1] op_sel_hi:[1,0]
	v_pk_mul_f32 v[194:195], v[122:123], v[0:1] op_sel_hi:[1,0]
	v_pk_mul_f32 v[196:197], v[124:125], v[0:1] op_sel_hi:[1,0]
	v_pk_mul_f32 v[210:211], v[118:119], v[0:1] op_sel_hi:[1,0]
	v_pk_mul_f32 v[212:213], v[120:121], v[0:1] op_sel_hi:[1,0]
	v_pk_mul_f32 v[214:215], v[114:115], v[0:1] op_sel_hi:[1,0]
	v_pk_mul_f32 v[216:217], v[116:117], v[0:1] op_sel_hi:[1,0]
	ds_bpermute_b32 v0, v188, v191
	s_waitcnt lgkmcnt(1)
; __device__ __forceinline__ unsigned cvt_pk_bf16(float lo, float hi) { unsigned r; asm volatile("v_cvt_pk_bf16_f32 %0, %1, %2" : "=v"(r) : "v"(lo), "v"(hi)); return r; }
;     __device__ __forceinline__ void operator()(const f32x4 (&acc)[2][2][4][2], const Unit& u, int wr, int wc, int fr, int fq) const {
;     ...
;                 ss += __shfl_xor(ss, 16); ss += __shfl_xor(ss, 32);
;                 const float rs = __builtin_amdgcn_rsqf((float)sq[ai][m] * (1.0f / (1024.0f * 1048576.0f)) + RMS_EPS);
;                 const float rn = rs * __builtin_amdgcn_rsqf(rs * rs * ss * (1.0f / 64.0f) + RMS_EPS);
; #pragma unroll
;                 for (int bj = 0; bj < 2; ++bj)
; #pragma unroll
;                     for (int n = 0; n < 2; ++n) v[bj][n] = v[bj][n] * rn * g[bj][n];
;                 const f32x4 c0 = *(const f32x4*)(cs + (size_t)row * 8), c1 = *(const f32x4*)(cs + (size_t)row * 8 + 4), s0 = *(const f32x4*)(sn + (size_t)row * 8), s1 = *(const f32x4*)(sn + (size_t)row * 8 + 4);
; #pragma unroll
;                 for (int n = 0; n < 2; ++n)
; #pragma unroll
;                     for (int j = 0; j < 4; ++j) { const float own = v[0][n][j], oth = __shfl_xor(own, 16); const float c = n ? c1[j] : c0[j], s = n ? s1[j] : s0[j];
;                         v[0][n][j] = rot ? (own * c + sgn * oth * s) : own; }
;                 bf16_t* rowp = base + (size_t)row * 1024 + col0;
; #pragma unroll
;                 for (int bj = 0; bj < 2; ++bj) { u32x4 w; w.x = cvt_pk_bf16(v[bj][0][0], v[bj][0][1]); w.y = cvt_pk_bf16(v[bj][0][2], v[bj][0][3]); w.z = cvt_pk_bf16(v[bj][1][0], v[bj][1][1]); w.w = cvt_pk_bf16(v[bj][1][2], v[bj][1][3]);
;                     *(u32x4*)(rowp + 32 * bj) = w; } }
	v_cndmask_b32_e64 v222, v222, -v222, s[0:1]
	v_mov_b32_e32 v224, v218
	v_mov_b32_e32 v223, v190
	v_pk_mul_f32 v[222:223], v[224:225], v[222:223]
	v_pk_mul_f32 v[192:193], v[160:161], v[192:193]
	v_add_f32_e32 v202, v222, v223
	v_cndmask_b32_e64 v218, v190, v202, s[4:5]
	s_waitcnt lgkmcnt(0)
	v_cndmask_b32_e64 v190, v0, -v0, s[0:1]
	ds_bpermute_b32 v0, v188, v192
	v_mov_b32_e32 v202, v219
	v_pk_mul_f32 v[202:203], v[202:203], v[190:191]
	v_pk_mul_f32 v[194:195], v[166:167], v[194:195]
	v_add_f32_e32 v190, v202, v203
	v_cndmask_b32_e64 v219, v191, v190, s[4:5]
	s_waitcnt lgkmcnt(0)
	v_cndmask_b32_e64 v190, v0, -v0, s[0:1]
	ds_bpermute_b32 v0, v188, v193
	v_mov_b32_e32 v202, v220
	v_mov_b32_e32 v203, v204
	v_mov_b32_e32 v191, v192
	v_pk_mul_f32 v[190:191], v[202:203], v[190:191]
	v_mov_b32_e32 v204, v221
	v_add_f32_e32 v190, v190, v191
	v_cndmask_b32_e64 v220, v192, v190, s[4:5]
	s_waitcnt lgkmcnt(0)
	v_cndmask_b32_e64 v192, v0, -v0, s[0:1]
	ds_bpermute_b32 v0, v188, v194
	v_pk_mul_f32 v[190:191], v[204:205], v[192:193]
	v_pk_mul_f32 v[196:197], v[164:165], v[196:197]
	v_add_f32_e32 v190, v190, v191
	v_cndmask_b32_e64 v204, v193, v190, s[4:5]
	s_waitcnt lgkmcnt(0)
	v_cndmask_b32_e64 v190, v0, -v0, s[0:1]
	ds_bpermute_b32 v0, v188, v195
	v_pk_mov_b32 v[202:203], v[196:197], v[194:195] op_sel:[1,0]
	v_mov_b32_e32 v192, v206
	v_mov_b32_e32 v193, v198
	v_mov_b32_e32 v191, v203
	v_pk_mul_f32 v[190:191], v[192:193], v[190:191]
	v_mov_b32_e32 v198, v207
	v_add_f32_e32 v190, v190, v191
	v_cndmask_b32_e64 v205, v194, v190, s[4:5]
	s_waitcnt lgkmcnt(0)
	v_cndmask_b32_e64 v194, v0, -v0, s[0:1]
	ds_bpermute_b32 v0, v188, v196
	v_pk_mul_f32 v[190:191], v[198:199], v[194:195]
	v_mov_b32_e32 v192, v208
	v_add_f32_e32 v190, v190, v191
	v_cndmask_b32_e64 v198, v195, v190, s[4:5]
	s_waitcnt lgkmcnt(0)
	v_cndmask_b32_e64 v190, v0, -v0, s[0:1]
	ds_bpermute_b32 v0, v188, v197
	v_mov_b32_e32 v193, v200
	v_mov_b32_e32 v191, v196
	v_pk_mul_f32 v[190:191], v[192:193], v[190:191]
	v_mov_b32_e32 v208, v201
	v_add_f32_e32 v190, v190, v191
	s_waitcnt lgkmcnt(0)
	v_cndmask_b32_e64 v203, v0, -v0, s[0:1]
	v_cndmask_b32_e64 v193, v196, v190, s[4:5]
	v_pk_mul_f32 v[190:191], v[208:209], v[202:203]
	v_pk_mul_f32 v[212:213], v[154:155], v[212:213]
	v_add_f32_e32 v0, v190, v191
	v_lshlrev_b64 v[190:191], 11, v[148:149]
	v_lshl_add_u64 v[194:195], v[150:151], 0, v[190:191]
	v_cvt_pk_bf16_f32 v190, v218, v219
	v_cvt_pk_bf16_f32 v191, v220, v204
	v_pk_mul_f32 v[210:211], v[168:169], v[210:211]
	v_cndmask_b32_e64 v0, v197, v0, s[4:5]
	v_cvt_pk_bf16_f32 v192, v205, v198
	v_cvt_pk_bf16_f32 v193, v193, v0
	global_store_dwordx4 v[194:195], v[190:193], off
	v_pk_mul_f32 v[216:217], v[156:157], v[216:217]
	v_pk_mul_f32 v[214:215], v[158:159], v[214:215]
	v_cvt_pk_bf16_f32 v190, v210, v211
	v_cvt_pk_bf16_f32 v191, v212, v213
	v_pk_mul_f32 v[206:207], v[112:113], v[112:113]
	v_cvt_pk_bf16_f32 v192, v214, v215
	v_cvt_pk_bf16_f32 v193, v216, v217
	global_store_dwordx4 v[194:195], v[190:193], off offset:64
	v_pk_mul_f32 v[208:209], v[110:111], v[110:111]
	v_mul_f32_e32 v0, v98, v98
	v_lshlrev_b64 v[190:191], 5, v[146:147]
	v_lshl_add_u64 v[198:199], s[24:25], 0, v[190:191]
	v_lshl_add_u64 v[202:203], s[26:27], 0, v[190:191]
	global_load_dwordx4 v[190:193], v[202:203], off
	global_load_dwordx4 v[194:197], v[198:199], off
	s_nop 0
	global_load_dwordx4 v[198:201], v[198:199], off offset:16
	s_nop 0
	global_load_dwordx4 v[202:205], v[202:203], off offset:16
	v_pk_mov_b32 v[210:211], v[208:209], v[206:207] op_sel:[1,0]
	v_mov_b32_e32 v209, v207
	v_pk_add_f32 v[206:207], v[210:211], v[208:209]
	v_pk_mul_f32 v[208:209], v[108:109], v[108:109]
	v_pk_mul_f32 v[210:211], v[106:107], v[106:107]
	v_pk_add_f32 v[206:207], v[206:207], v[206:207] op_sel:[0,1] op_sel_hi:[1,0]
	v_pk_mov_b32 v[212:213], v[210:211], v[208:209] op_sel:[1,0]
	v_mov_b32_e32 v211, v209
	v_pk_add_f32 v[208:209], v[212:213], v[210:211]
	v_mul_f32_e32 v210, v99, v99
	v_pk_add_f32 v[208:209], v[208:209], v[208:209] op_sel:[0,1] op_sel_hi:[1,0]
	v_mov_b32_e32 v207, v0
	v_mov_b32_e32 v209, v210
	v_mul_f32_e32 v0, v103, v103
	v_mul_f32_e32 v211, v100, v100
	v_pk_add_f32 v[206:207], v[206:207], v[208:209]
	v_pk_fma_f32 v[208:209], v[102:103], v[102:103], v[0:1] op_sel_hi:[1,1,0]
	v_mul_f32_e32 v0, v105, v105
	v_mul_f32_e32 v212, v101, v101
	v_mov_b32_e32 v209, v211
	v_pk_fma_f32 v[210:211], v[104:105], v[104:105], v[0:1] op_sel_hi:[1,1,0]
	s_waitcnt vmcnt(3)
	v_mov_b32_e32 v222, v190
	v_mov_b32_e32 v211, v212
	v_pk_add_f32 v[208:209], v[208:209], v[210:211]
	s_waitcnt vmcnt(2)
	v_mov_b32_e32 v223, v194
	v_pk_add_f32 v[206:207], v[206:207], v[208:209]
	v_mov_b32_e32 v194, v191
	v_add_f32_e32 v0, v206, v207
	v_ffbh_u32_e32 v207, v181
	v_min_u32_e32 v207, 32, v207
	v_lshlrev_b64 v[180:181], v207, v[180:181]
	ds_bpermute_b32 v206, v188, v0
	v_min_u32_e32 v180, 1, v180
	v_or_b32_e32 v180, v181, v180
	v_cvt_f32_u32_e32 v180, v180
	s_waitcnt lgkmcnt(0)
	v_add_f32_e32 v0, v0, v206
	v_sub_u32_e32 v206, 32, v207
	v_ldexp_f32 v180, v180, v206
	v_mov_b32_e32 v181, v0
	s_nop 1
	v_permlane32_swap_b32_e32 v181, v0
	v_fmamk_f32 v180, v180, 0x30800000, v240
	v_rsq_f32_e32 v180, v180
	s_waitcnt lgkmcnt(0)
	v_add_f32_e32 v0, v0, v181
	v_mul_f32_e32 v181, v180, v180
	v_mul_f32_e32 v0, v181, v0
	v_fmamk_f32 v0, v0, 0x3c800000, v240
	v_rsq_f32_e32 v0, v0
	s_nop 0
	v_mul_f32_e32 v0, v180, v0
	v_pk_mul_f32 v[180:181], v[110:111], v[0:1] op_sel_hi:[1,0]
	v_pk_mul_f32 v[206:207], v[112:113], v[0:1] op_sel_hi:[1,0]
	v_pk_mul_f32 v[180:181], v[162:163], v[180:181]
	ds_bpermute_b32 v220, v188, v180
	v_pk_mul_f32 v[208:209], v[106:107], v[0:1] op_sel_hi:[1,0]
	v_pk_mul_f32 v[210:211], v[108:109], v[0:1] op_sel_hi:[1,0]
	v_pk_mul_f32 v[212:213], v[102:103], v[0:1] op_sel_hi:[1,0]
	v_pk_mul_f32 v[214:215], v[104:105], v[0:1] op_sel_hi:[1,0]
	v_pk_mul_f32 v[216:217], v[98:99], v[0:1] op_sel_hi:[1,0]
	v_pk_mul_f32 v[218:219], v[100:101], v[0:1] op_sel_hi:[1,0]
	ds_bpermute_b32 v0, v188, v181
	s_waitcnt lgkmcnt(1)
; __device__ __forceinline__ unsigned cvt_pk_bf16(float lo, float hi) { unsigned r; asm volatile("v_cvt_pk_bf16_f32 %0, %1, %2" : "=v"(r) : "v"(lo), "v"(hi)); return r; }
;     __device__ __forceinline__ void operator()(const f32x4 (&acc)[2][2][4][2], const Unit& u, int wr, int wc, int fr, int fq) const {
;     ...
;                 ss += __shfl_xor(ss, 16); ss += __shfl_xor(ss, 32);
;                 const float rs = __builtin_amdgcn_rsqf((float)sq[ai][m] * (1.0f / (1024.0f * 1048576.0f)) + RMS_EPS);
;                 const float rn = rs * __builtin_amdgcn_rsqf(rs * rs * ss * (1.0f / 64.0f) + RMS_EPS);
; #pragma unroll
;                 for (int bj = 0; bj < 2; ++bj)
; #pragma unroll
;                     for (int n = 0; n < 2; ++n) v[bj][n] = v[bj][n] * rn * g[bj][n];
;                 const f32x4 c0 = *(const f32x4*)(cs + (size_t)row * 8), c1 = *(const f32x4*)(cs + (size_t)row * 8 + 4), s0 = *(const f32x4*)(sn + (size_t)row * 8), s1 = *(const f32x4*)(sn + (size_t)row * 8 + 4);
; #pragma unroll
;                 for (int n = 0; n < 2; ++n)
; #pragma unroll
;                     for (int j = 0; j < 4; ++j) { const float own = v[0][n][j], oth = __shfl_xor(own, 16); const float c = n ? c1[j] : c0[j], s = n ? s1[j] : s0[j];
;                         v[0][n][j] = rot ? (own * c + sgn * oth * s) : own; }
;                 bf16_t* rowp = base + (size_t)row * 1024 + col0;
; #pragma unroll
;                 for (int bj = 0; bj < 2; ++bj) { u32x4 w; w.x = cvt_pk_bf16(v[bj][0][0], v[bj][0][1]); w.y = cvt_pk_bf16(v[bj][0][2], v[bj][0][3]); w.z = cvt_pk_bf16(v[bj][1][0], v[bj][1][1]); w.w = cvt_pk_bf16(v[bj][1][2], v[bj][1][3]);
;                     *(u32x4*)(rowp + 32 * bj) = w; } }
	v_cndmask_b32_e64 v220, v220, -v220, s[0:1]
	v_mov_b32_e32 v221, v180
	v_pk_mul_f32 v[220:221], v[222:223], v[220:221]
	v_pk_mul_f32 v[206:207], v[160:161], v[206:207]
	v_add_f32_e32 v190, v220, v221
	v_cndmask_b32_e64 v220, v180, v190, s[4:5]
	s_waitcnt lgkmcnt(0)
	v_cndmask_b32_e64 v180, v0, -v0, s[0:1]
	ds_bpermute_b32 v0, v188, v206
	v_pk_mul_f32 v[190:191], v[194:195], v[180:181]
	v_pk_mul_f32 v[208:209], v[166:167], v[208:209]
	v_add_f32_e32 v180, v190, v191
	v_cndmask_b32_e64 v194, v181, v180, s[4:5]
	s_waitcnt lgkmcnt(0)
	v_cndmask_b32_e64 v180, v0, -v0, s[0:1]
	ds_bpermute_b32 v0, v188, v207
	v_mov_b32_e32 v190, v192
	v_mov_b32_e32 v191, v196
	v_mov_b32_e32 v181, v206
	v_pk_mul_f32 v[180:181], v[190:191], v[180:181]
	v_mov_b32_e32 v196, v193
	v_add_f32_e32 v180, v180, v181
	v_cndmask_b32_e64 v195, v206, v180, s[4:5]
	s_waitcnt lgkmcnt(0)
	v_cndmask_b32_e64 v206, v0, -v0, s[0:1]
	ds_bpermute_b32 v0, v188, v208
	v_pk_mul_f32 v[180:181], v[196:197], v[206:207]
	v_pk_mul_f32 v[210:211], v[164:165], v[210:211]
	v_add_f32_e32 v180, v180, v181
	v_cndmask_b32_e64 v196, v207, v180, s[4:5]
	s_waitcnt lgkmcnt(0)
	v_cndmask_b32_e64 v180, v0, -v0, s[0:1]
	ds_bpermute_b32 v0, v188, v209
	v_pk_mov_b32 v[192:193], v[210:211], v[208:209] op_sel:[1,0]
	s_waitcnt vmcnt(0)
	v_mov_b32_e32 v190, v202
	v_mov_b32_e32 v191, v198
	v_mov_b32_e32 v181, v193
	v_pk_mul_f32 v[180:181], v[190:191], v[180:181]
	v_mov_b32_e32 v198, v203
	v_add_f32_e32 v180, v180, v181
	v_cndmask_b32_e64 v197, v208, v180, s[4:5]
	s_waitcnt lgkmcnt(0)
	v_cndmask_b32_e64 v208, v0, -v0, s[0:1]
	ds_bpermute_b32 v0, v188, v210
	v_pk_mul_f32 v[180:181], v[198:199], v[208:209]
	v_mov_b32_e32 v190, v204
	v_add_f32_e32 v180, v180, v181
	v_cndmask_b32_e64 v198, v209, v180, s[4:5]
	s_waitcnt lgkmcnt(0)
	v_cndmask_b32_e64 v180, v0, -v0, s[0:1]
	ds_bpermute_b32 v0, v188, v211
	v_mov_b32_e32 v191, v200
	v_mov_b32_e32 v181, v210
	v_pk_mul_f32 v[180:181], v[190:191], v[180:181]
	v_mov_b32_e32 v204, v201
	v_add_f32_e32 v180, v180, v181
	s_waitcnt lgkmcnt(0)
	v_cndmask_b32_e64 v193, v0, -v0, s[0:1]
	v_cndmask_b32_e64 v199, v210, v180, s[4:5]
	v_pk_mul_f32 v[180:181], v[204:205], v[192:193]
	v_cvt_pk_bf16_f32 v190, v220, v194
	v_cvt_pk_bf16_f32 v191, v195, v196
	v_cvt_pk_bf16_f32 v192, v197, v198
	v_pk_mul_f32 v[214:215], v[154:155], v[214:215]
	v_add_f32_e32 v0, v180, v181
	v_lshlrev_b64 v[180:181], 11, v[146:147]
	v_cndmask_b32_e64 v0, v211, v0, s[4:5]
	v_lshl_add_u64 v[180:181], v[150:151], 0, v[180:181]
	v_cvt_pk_bf16_f32 v193, v199, v0
	v_pk_mul_f32 v[212:213], v[168:169], v[212:213]
	v_pk_mul_f32 v[218:219], v[156:157], v[218:219]
	v_pk_mul_f32 v[216:217], v[158:159], v[216:217]
	global_store_dwordx4 v[180:181], v[190:193], off
	v_pk_mul_f32 v[206:207], v[94:95], v[94:95]
	v_mul_f32_e32 v0, v82, v82
	v_cvt_pk_bf16_f32 v190, v212, v213
	v_cvt_pk_bf16_f32 v191, v214, v215
	v_cvt_pk_bf16_f32 v192, v216, v217
	v_cvt_pk_bf16_f32 v193, v218, v219
	global_store_dwordx4 v[180:181], v[190:193], off offset:64
	v_lshlrev_b64 v[180:181], 5, v[144:145]
	v_lshl_add_u64 v[198:199], s[24:25], 0, v[180:181]
	v_lshl_add_u64 v[180:181], s[26:27], 0, v[180:181]
	global_load_dwordx4 v[190:193], v[180:181], off
	global_load_dwordx4 v[194:197], v[198:199], off
	s_nop 0
	global_load_dwordx4 v[198:201], v[198:199], off offset:16
	s_nop 0
	global_load_dwordx4 v[202:205], v[180:181], off offset:16
	v_pk_mul_f32 v[180:181], v[96:97], v[96:97]
	s_waitcnt vmcnt(3)
	v_mov_b32_e32 v220, v190
	v_pk_mov_b32 v[208:209], v[206:207], v[180:181] op_sel:[1,0]
	v_mov_b32_e32 v207, v181
	v_pk_add_f32 v[180:181], v[208:209], v[206:207]
	v_pk_mul_f32 v[206:207], v[92:93], v[92:93]
	v_pk_mul_f32 v[208:209], v[90:91], v[90:91]
	v_pk_add_f32 v[180:181], v[180:181], v[180:181] op_sel:[0,1] op_sel_hi:[1,0]
	v_pk_mov_b32 v[210:211], v[208:209], v[206:207] op_sel:[1,0]
	v_mov_b32_e32 v209, v207
	v_pk_add_f32 v[206:207], v[210:211], v[208:209]
	v_mul_f32_e32 v208, v83, v83
	v_pk_add_f32 v[206:207], v[206:207], v[206:207] op_sel:[0,1] op_sel_hi:[1,0]
	v_mov_b32_e32 v181, v0
	v_mov_b32_e32 v207, v208
	v_mul_f32_e32 v0, v87, v87
	v_mul_f32_e32 v209, v84, v84
	v_pk_add_f32 v[180:181], v[180:181], v[206:207]
	v_pk_fma_f32 v[206:207], v[86:87], v[86:87], v[0:1] op_sel_hi:[1,1,0]
	v_mul_f32_e32 v0, v89, v89
	v_mul_f32_e32 v210, v85, v85
	v_mov_b32_e32 v207, v209
	v_pk_fma_f32 v[208:209], v[88:89], v[88:89], v[0:1] op_sel_hi:[1,1,0]
	s_waitcnt vmcnt(2)
	v_mov_b32_e32 v221, v194
	v_mov_b32_e32 v209, v210
	v_pk_add_f32 v[206:207], v[206:207], v[208:209]
	v_mov_b32_e32 v194, v191
	v_pk_add_f32 v[180:181], v[180:181], v[206:207]
	s_nop 0
	v_add_f32_e32 v0, v180, v181
	v_ffbh_u32_e32 v181, v179
	v_min_u32_e32 v181, 32, v181
	v_lshlrev_b64 v[178:179], v181, v[178:179]
	ds_bpermute_b32 v180, v188, v0
	v_min_u32_e32 v178, 1, v178
	v_or_b32_e32 v178, v179, v178
	v_cvt_f32_u32_e32 v178, v178
	s_waitcnt lgkmcnt(0)
	v_add_f32_e32 v0, v0, v180
	v_sub_u32_e32 v180, 32, v181
	v_ldexp_f32 v178, v178, v180
	v_mov_b32_e32 v179, v0
	s_nop 1
	v_permlane32_swap_b32_e32 v179, v0
	v_fmamk_f32 v178, v178, 0x30800000, v240
	v_rsq_f32_e32 v178, v178
	s_waitcnt lgkmcnt(0)
	v_add_f32_e32 v0, v0, v179
	v_mul_f32_e32 v179, v178, v178
	v_mul_f32_e32 v0, v179, v0
	v_fmamk_f32 v0, v0, 0x3c800000, v240
	v_rsq_f32_e32 v0, v0
	s_nop 0
	v_mul_f32_e32 v0, v178, v0
	v_pk_mul_f32 v[178:179], v[94:95], v[0:1] op_sel_hi:[1,0]
	v_pk_mul_f32 v[180:181], v[96:97], v[0:1] op_sel_hi:[1,0]
	v_pk_mul_f32 v[178:179], v[162:163], v[178:179]
	ds_bpermute_b32 v218, v188, v178
	v_pk_mul_f32 v[206:207], v[90:91], v[0:1] op_sel_hi:[1,0]
	v_pk_mul_f32 v[208:209], v[92:93], v[0:1] op_sel_hi:[1,0]
	v_pk_mul_f32 v[210:211], v[86:87], v[0:1] op_sel_hi:[1,0]
	v_pk_mul_f32 v[212:213], v[88:89], v[0:1] op_sel_hi:[1,0]
	v_pk_mul_f32 v[214:215], v[82:83], v[0:1] op_sel_hi:[1,0]
	v_pk_mul_f32 v[216:217], v[84:85], v[0:1] op_sel_hi:[1,0]
	ds_bpermute_b32 v0, v188, v179
	s_waitcnt lgkmcnt(1)
; __device__ __forceinline__ unsigned cvt_pk_bf16(float lo, float hi) { unsigned r; asm volatile("v_cvt_pk_bf16_f32 %0, %1, %2" : "=v"(r) : "v"(lo), "v"(hi)); return r; }
;     __device__ __forceinline__ void operator()(const f32x4 (&acc)[2][2][4][2], const Unit& u, int wr, int wc, int fr, int fq) const {
;     ...
;                 ss += __shfl_xor(ss, 16); ss += __shfl_xor(ss, 32);
;                 const float rs = __builtin_amdgcn_rsqf((float)sq[ai][m] * (1.0f / (1024.0f * 1048576.0f)) + RMS_EPS);
;                 const float rn = rs * __builtin_amdgcn_rsqf(rs * rs * ss * (1.0f / 64.0f) + RMS_EPS);
; #pragma unroll
;                 for (int bj = 0; bj < 2; ++bj)
; #pragma unroll
;                     for (int n = 0; n < 2; ++n) v[bj][n] = v[bj][n] * rn * g[bj][n];
;                 const f32x4 c0 = *(const f32x4*)(cs + (size_t)row * 8), c1 = *(const f32x4*)(cs + (size_t)row * 8 + 4), s0 = *(const f32x4*)(sn + (size_t)row * 8), s1 = *(const f32x4*)(sn + (size_t)row * 8 + 4);
; #pragma unroll
;                 for (int n = 0; n < 2; ++n)
; #pragma unroll
;                     for (int j = 0; j < 4; ++j) { const float own = v[0][n][j], oth = __shfl_xor(own, 16); const float c = n ? c1[j] : c0[j], s = n ? s1[j] : s0[j];
;                         v[0][n][j] = rot ? (own * c + sgn * oth * s) : own; }
;                 bf16_t* rowp = base + (size_t)row * 1024 + col0;
; #pragma unroll
;                 for (int bj = 0; bj < 2; ++bj) { u32x4 w; w.x = cvt_pk_bf16(v[bj][0][0], v[bj][0][1]); w.y = cvt_pk_bf16(v[bj][0][2], v[bj][0][3]); w.z = cvt_pk_bf16(v[bj][1][0], v[bj][1][1]); w.w = cvt_pk_bf16(v[bj][1][2], v[bj][1][3]);
;                     *(u32x4*)(rowp + 32 * bj) = w; } }
	v_cndmask_b32_e64 v218, v218, -v218, s[0:1]
	v_mov_b32_e32 v219, v178
	v_pk_mul_f32 v[218:219], v[220:221], v[218:219]
	v_pk_mul_f32 v[180:181], v[160:161], v[180:181]
	v_add_f32_e32 v190, v218, v219
	v_cndmask_b32_e64 v218, v178, v190, s[4:5]
	s_waitcnt lgkmcnt(0)
	v_cndmask_b32_e64 v178, v0, -v0, s[0:1]
	ds_bpermute_b32 v0, v188, v180
	v_pk_mul_f32 v[190:191], v[194:195], v[178:179]
	v_pk_mul_f32 v[206:207], v[166:167], v[206:207]
	v_add_f32_e32 v178, v190, v191
	v_cndmask_b32_e64 v194, v179, v178, s[4:5]
	s_waitcnt lgkmcnt(0)
	v_cndmask_b32_e64 v178, v0, -v0, s[0:1]
	ds_bpermute_b32 v0, v188, v181
	v_mov_b32_e32 v190, v192
	v_mov_b32_e32 v191, v196
	v_mov_b32_e32 v179, v180
	v_pk_mul_f32 v[178:179], v[190:191], v[178:179]
	v_mov_b32_e32 v196, v193
	v_add_f32_e32 v178, v178, v179
	v_cndmask_b32_e64 v192, v180, v178, s[4:5]
	s_waitcnt lgkmcnt(0)
	v_cndmask_b32_e64 v180, v0, -v0, s[0:1]
	ds_bpermute_b32 v0, v188, v206
	v_pk_mul_f32 v[178:179], v[196:197], v[180:181]
	v_pk_mul_f32 v[208:209], v[164:165], v[208:209]
	v_add_f32_e32 v178, v178, v179
	v_cndmask_b32_e64 v193, v181, v178, s[4:5]
	s_waitcnt lgkmcnt(0)
	v_cndmask_b32_e64 v178, v0, -v0, s[0:1]
	ds_bpermute_b32 v0, v188, v207
	v_pk_mov_b32 v[190:191], v[208:209], v[206:207] op_sel:[1,0]
	s_waitcnt vmcnt(0)
	v_mov_b32_e32 v180, v202
	v_mov_b32_e32 v181, v198
	v_mov_b32_e32 v179, v191
	v_pk_mul_f32 v[178:179], v[180:181], v[178:179]
	v_mov_b32_e32 v198, v203
	v_add_f32_e32 v178, v178, v179
	v_cndmask_b32_e64 v195, v206, v178, s[4:5]
	s_waitcnt lgkmcnt(0)
	v_cndmask_b32_e64 v206, v0, -v0, s[0:1]
	ds_bpermute_b32 v0, v188, v208
	v_pk_mul_f32 v[178:179], v[198:199], v[206:207]
	v_mov_b32_e32 v180, v204
	v_add_f32_e32 v178, v178, v179
	v_cndmask_b32_e64 v196, v207, v178, s[4:5]
	s_waitcnt lgkmcnt(0)
	v_cndmask_b32_e64 v178, v0, -v0, s[0:1]
	ds_bpermute_b32 v0, v188, v209
	v_mov_b32_e32 v181, v200
	v_mov_b32_e32 v179, v208
	v_pk_mul_f32 v[178:179], v[180:181], v[178:179]
	v_mov_b32_e32 v204, v201
	v_add_f32_e32 v178, v178, v179
	s_waitcnt lgkmcnt(0)
	v_cndmask_b32_e64 v191, v0, -v0, s[0:1]
	v_cndmask_b32_e64 v181, v208, v178, s[4:5]
	v_pk_mul_f32 v[178:179], v[204:205], v[190:191]
	v_pk_mul_f32 v[212:213], v[154:155], v[212:213]
	v_add_f32_e32 v0, v178, v179
	v_lshlrev_b64 v[178:179], 11, v[144:145]
	v_lshl_add_u64 v[190:191], v[150:151], 0, v[178:179]
	v_cvt_pk_bf16_f32 v178, v218, v194
	v_cvt_pk_bf16_f32 v179, v192, v193
	v_pk_mul_f32 v[210:211], v[168:169], v[210:211]
	v_cndmask_b32_e64 v0, v209, v0, s[4:5]
	v_cvt_pk_bf16_f32 v180, v195, v196
	v_cvt_pk_bf16_f32 v181, v181, v0
	global_store_dwordx4 v[190:191], v[178:181], off
	v_pk_mul_f32 v[216:217], v[156:157], v[216:217]
	v_pk_mul_f32 v[214:215], v[158:159], v[214:215]
	v_cvt_pk_bf16_f32 v178, v210, v211
	v_cvt_pk_bf16_f32 v179, v212, v213
	v_pk_mul_f32 v[202:203], v[80:81], v[80:81]
	v_cvt_pk_bf16_f32 v180, v214, v215
	v_cvt_pk_bf16_f32 v181, v216, v217
	global_store_dwordx4 v[190:191], v[178:181], off offset:64
	v_pk_mul_f32 v[204:205], v[78:79], v[78:79]
	v_mul_f32_e32 v0, v66, v66
	v_lshlrev_b64 v[178:179], 5, v[142:143]
	v_lshl_add_u64 v[194:195], s[24:25], 0, v[178:179]
	v_lshl_add_u64 v[198:199], s[26:27], 0, v[178:179]
	global_load_dwordx4 v[178:181], v[198:199], off
	global_load_dwordx4 v[190:193], v[194:195], off
	s_nop 0
	global_load_dwordx4 v[194:197], v[194:195], off offset:16
	s_nop 0
	global_load_dwordx4 v[198:201], v[198:199], off offset:16
	v_pk_mov_b32 v[206:207], v[204:205], v[202:203] op_sel:[1,0]
	v_mov_b32_e32 v205, v203
	v_pk_add_f32 v[202:203], v[206:207], v[204:205]
	v_pk_mul_f32 v[204:205], v[76:77], v[76:77]
	v_pk_mul_f32 v[206:207], v[74:75], v[74:75]
	v_pk_add_f32 v[202:203], v[202:203], v[202:203] op_sel:[0,1] op_sel_hi:[1,0]
	v_pk_mov_b32 v[208:209], v[206:207], v[204:205] op_sel:[1,0]
	v_mov_b32_e32 v207, v205
	v_pk_add_f32 v[204:205], v[208:209], v[206:207]
	v_mul_f32_e32 v206, v67, v67
	v_pk_add_f32 v[204:205], v[204:205], v[204:205] op_sel:[0,1] op_sel_hi:[1,0]
	v_mov_b32_e32 v203, v0
	v_mov_b32_e32 v205, v206
	v_mul_f32_e32 v0, v71, v71
	v_mul_f32_e32 v207, v68, v68
	v_pk_add_f32 v[202:203], v[202:203], v[204:205]
	v_pk_fma_f32 v[204:205], v[70:71], v[70:71], v[0:1] op_sel_hi:[1,1,0]
	v_mul_f32_e32 v0, v73, v73
	v_mul_f32_e32 v208, v69, v69
	v_mov_b32_e32 v205, v207
	v_pk_fma_f32 v[206:207], v[72:73], v[72:73], v[0:1] op_sel_hi:[1,1,0]
	s_waitcnt vmcnt(3)
	v_mov_b32_e32 v220, v178
	v_mov_b32_e32 v207, v208
	v_pk_add_f32 v[204:205], v[204:205], v[206:207]
	s_waitcnt vmcnt(2)
	v_mov_b32_e32 v221, v190
	v_pk_add_f32 v[202:203], v[202:203], v[204:205]
	v_mov_b32_e32 v190, v179
	v_add_f32_e32 v0, v202, v203
	v_ffbh_u32_e32 v203, v177
	v_min_u32_e32 v203, 32, v203
	v_lshlrev_b64 v[176:177], v203, v[176:177]
	ds_bpermute_b32 v202, v188, v0
	v_min_u32_e32 v176, 1, v176
	v_or_b32_e32 v176, v177, v176
	v_cvt_f32_u32_e32 v176, v176
	s_waitcnt lgkmcnt(0)
	v_add_f32_e32 v0, v0, v202
	v_sub_u32_e32 v202, 32, v203
	v_ldexp_f32 v176, v176, v202
	v_mov_b32_e32 v177, v0
	s_nop 1
	v_permlane32_swap_b32_e32 v177, v0
	v_fmamk_f32 v176, v176, 0x30800000, v240
	v_rsq_f32_e32 v202, v176
	s_waitcnt lgkmcnt(0)
	v_add_f32_e32 v0, v0, v177
	v_mul_f32_e32 v176, v202, v202
	v_mul_f32_e32 v0, v176, v0
	v_fmamk_f32 v0, v0, 0x3c800000, v240
	v_rsq_f32_e32 v0, v0
	v_add_u32_e32 v176, 0x80, v148
	v_ashrrev_i32_e32 v177, 31, v176
	v_mul_f32_e32 v0, v202, v0
	v_pk_mul_f32 v[202:203], v[78:79], v[0:1] op_sel_hi:[1,0]
	v_pk_mul_f32 v[204:205], v[80:81], v[0:1] op_sel_hi:[1,0]
	v_pk_mul_f32 v[202:203], v[162:163], v[202:203]
	ds_bpermute_b32 v218, v188, v202
	v_pk_mul_f32 v[206:207], v[74:75], v[0:1] op_sel_hi:[1,0]
	v_pk_mul_f32 v[208:209], v[76:77], v[0:1] op_sel_hi:[1,0]
	v_pk_mul_f32 v[210:211], v[70:71], v[0:1] op_sel_hi:[1,0]
	v_pk_mul_f32 v[212:213], v[72:73], v[0:1] op_sel_hi:[1,0]
	v_pk_mul_f32 v[214:215], v[66:67], v[0:1] op_sel_hi:[1,0]
	v_pk_mul_f32 v[216:217], v[68:69], v[0:1] op_sel_hi:[1,0]
	ds_bpermute_b32 v0, v188, v203
	s_waitcnt lgkmcnt(1)
; __device__ __forceinline__ unsigned cvt_pk_bf16(float lo, float hi) { unsigned r; asm volatile("v_cvt_pk_bf16_f32 %0, %1, %2" : "=v"(r) : "v"(lo), "v"(hi)); return r; }
;     __device__ __forceinline__ void operator()(const f32x4 (&acc)[2][2][4][2], const Unit& u, int wr, int wc, int fr, int fq) const {
;     ...
;                 ss += __shfl_xor(ss, 16); ss += __shfl_xor(ss, 32);
;                 const float rs = __builtin_amdgcn_rsqf((float)sq[ai][m] * (1.0f / (1024.0f * 1048576.0f)) + RMS_EPS);
;                 const float rn = rs * __builtin_amdgcn_rsqf(rs * rs * ss * (1.0f / 64.0f) + RMS_EPS);
; #pragma unroll
;                 for (int bj = 0; bj < 2; ++bj)
; #pragma unroll
;                     for (int n = 0; n < 2; ++n) v[bj][n] = v[bj][n] * rn * g[bj][n];
;                 const f32x4 c0 = *(const f32x4*)(cs + (size_t)row * 8), c1 = *(const f32x4*)(cs + (size_t)row * 8 + 4), s0 = *(const f32x4*)(sn + (size_t)row * 8), s1 = *(const f32x4*)(sn + (size_t)row * 8 + 4);
; #pragma unroll
;                 for (int n = 0; n < 2; ++n)
; #pragma unroll
;                     for (int j = 0; j < 4; ++j) { const float own = v[0][n][j], oth = __shfl_xor(own, 16); const float c = n ? c1[j] : c0[j], s = n ? s1[j] : s0[j];
;                         v[0][n][j] = rot ? (own * c + sgn * oth * s) : own; }
;                 bf16_t* rowp = base + (size_t)row * 1024 + col0;
; #pragma unroll
;                 for (int bj = 0; bj < 2; ++bj) { u32x4 w; w.x = cvt_pk_bf16(v[bj][0][0], v[bj][0][1]); w.y = cvt_pk_bf16(v[bj][0][2], v[bj][0][3]); w.z = cvt_pk_bf16(v[bj][1][0], v[bj][1][1]); w.w = cvt_pk_bf16(v[bj][1][2], v[bj][1][3]);
;                     *(u32x4*)(rowp + 32 * bj) = w; } }
	v_cndmask_b32_e64 v218, v218, -v218, s[0:1]
	v_mov_b32_e32 v219, v202
	v_pk_mul_f32 v[218:219], v[220:221], v[218:219]
	v_pk_mul_f32 v[204:205], v[160:161], v[204:205]
	v_add_f32_e32 v178, v218, v219
	v_cndmask_b32_e64 v218, v202, v178, s[4:5]
	s_waitcnt lgkmcnt(0)
	v_cndmask_b32_e64 v202, v0, -v0, s[0:1]
	ds_bpermute_b32 v0, v188, v204
	v_pk_mul_f32 v[178:179], v[190:191], v[202:203]
	v_mov_b32_e32 v190, v180
	v_add_f32_e32 v178, v178, v179
	v_cndmask_b32_e64 v202, v203, v178, s[4:5]
	s_waitcnt lgkmcnt(0)
	v_cndmask_b32_e64 v178, v0, -v0, s[0:1]
	ds_bpermute_b32 v0, v188, v205
	v_mov_b32_e32 v191, v192
	v_mov_b32_e32 v179, v204
	v_pk_mul_f32 v[178:179], v[190:191], v[178:179]
	v_pk_mul_f32 v[206:207], v[166:167], v[206:207]
	v_add_f32_e32 v178, v178, v179
	v_cndmask_b32_e64 v203, v204, v178, s[4:5]
	s_waitcnt lgkmcnt(0)
	v_cndmask_b32_e64 v204, v0, -v0, s[0:1]
	ds_bpermute_b32 v0, v188, v206
	v_mov_b32_e32 v192, v181
	v_pk_mul_f32 v[178:179], v[192:193], v[204:205]
	v_pk_mul_f32 v[208:209], v[164:165], v[208:209]
	v_add_f32_e32 v178, v178, v179
	v_cndmask_b32_e64 v192, v205, v178, s[4:5]
	s_waitcnt lgkmcnt(0)
	v_cndmask_b32_e64 v178, v0, -v0, s[0:1]
	ds_bpermute_b32 v0, v188, v207
	v_pk_mov_b32 v[190:191], v[208:209], v[206:207] op_sel:[1,0]
	s_waitcnt vmcnt(0)
	v_mov_b32_e32 v180, v198
	v_mov_b32_e32 v181, v194
	v_mov_b32_e32 v179, v191
	v_pk_mul_f32 v[178:179], v[180:181], v[178:179]
	v_mov_b32_e32 v194, v199
	v_add_f32_e32 v178, v178, v179
	v_cndmask_b32_e64 v193, v206, v178, s[4:5]
	s_waitcnt lgkmcnt(0)
	v_cndmask_b32_e64 v206, v0, -v0, s[0:1]
	ds_bpermute_b32 v0, v188, v208
	v_pk_mul_f32 v[178:179], v[194:195], v[206:207]
	v_mov_b32_e32 v180, v200
	v_add_f32_e32 v178, v178, v179
	v_cndmask_b32_e64 v194, v207, v178, s[4:5]
	s_waitcnt lgkmcnt(0)
	v_cndmask_b32_e64 v178, v0, -v0, s[0:1]
	ds_bpermute_b32 v0, v188, v209
	v_mov_b32_e32 v181, v196
	v_mov_b32_e32 v179, v208
	v_pk_mul_f32 v[178:179], v[180:181], v[178:179]
	v_mov_b32_e32 v200, v197
	v_add_f32_e32 v178, v178, v179
	s_waitcnt lgkmcnt(0)
	v_cndmask_b32_e64 v191, v0, -v0, s[0:1]
	v_cndmask_b32_e64 v181, v208, v178, s[4:5]
	v_pk_mul_f32 v[178:179], v[200:201], v[190:191]
	v_pk_mul_f32 v[212:213], v[154:155], v[212:213]
	v_add_f32_e32 v0, v178, v179
	v_lshlrev_b64 v[178:179], 11, v[142:143]
	v_lshl_add_u64 v[190:191], v[150:151], 0, v[178:179]
	v_cvt_pk_bf16_f32 v178, v218, v202
	v_cvt_pk_bf16_f32 v179, v203, v192
	v_pk_mul_f32 v[210:211], v[168:169], v[210:211]
	v_cndmask_b32_e64 v0, v209, v0, s[4:5]
	v_cvt_pk_bf16_f32 v180, v193, v194
	v_cvt_pk_bf16_f32 v181, v181, v0
	global_store_dwordx4 v[190:191], v[178:181], off
	v_pk_mul_f32 v[216:217], v[156:157], v[216:217]
	v_pk_mul_f32 v[214:215], v[158:159], v[214:215]
	v_cvt_pk_bf16_f32 v178, v210, v211
	v_cvt_pk_bf16_f32 v179, v212, v213
	v_pk_mul_f32 v[202:203], v[64:65], v[64:65]
	v_cvt_pk_bf16_f32 v180, v214, v215
	v_cvt_pk_bf16_f32 v181, v216, v217
	global_store_dwordx4 v[190:191], v[178:181], off offset:64
	v_pk_mul_f32 v[204:205], v[62:63], v[62:63]
	v_mul_f32_e32 v0, v50, v50
	v_lshlrev_b64 v[178:179], 5, v[176:177]
	v_lshl_add_u64 v[194:195], s[24:25], 0, v[178:179]
	v_lshl_add_u64 v[198:199], s[26:27], 0, v[178:179]
	global_load_dwordx4 v[178:181], v[198:199], off
	global_load_dwordx4 v[190:193], v[194:195], off
	s_nop 0
	global_load_dwordx4 v[194:197], v[194:195], off offset:16
	s_nop 0
	global_load_dwordx4 v[198:201], v[198:199], off offset:16
	v_pk_mov_b32 v[206:207], v[204:205], v[202:203] op_sel:[1,0]
	v_mov_b32_e32 v205, v203
	v_pk_add_f32 v[202:203], v[206:207], v[204:205]
	v_pk_mul_f32 v[204:205], v[60:61], v[60:61]
	v_pk_mul_f32 v[206:207], v[58:59], v[58:59]
	v_pk_add_f32 v[202:203], v[202:203], v[202:203] op_sel:[0,1] op_sel_hi:[1,0]
	v_pk_mov_b32 v[208:209], v[206:207], v[204:205] op_sel:[1,0]
	v_mov_b32_e32 v207, v205
	v_pk_add_f32 v[204:205], v[208:209], v[206:207]
	v_mul_f32_e32 v206, v51, v51
	v_pk_add_f32 v[204:205], v[204:205], v[204:205] op_sel:[0,1] op_sel_hi:[1,0]
	v_mov_b32_e32 v203, v0
	v_mov_b32_e32 v205, v206
	v_mul_f32_e32 v0, v55, v55
	v_mul_f32_e32 v207, v52, v52
	v_pk_add_f32 v[202:203], v[202:203], v[204:205]
	v_pk_fma_f32 v[204:205], v[54:55], v[54:55], v[0:1] op_sel_hi:[1,1,0]
	v_mul_f32_e32 v0, v57, v57
	v_mul_f32_e32 v208, v53, v53
	v_mov_b32_e32 v205, v207
	v_pk_fma_f32 v[206:207], v[56:57], v[56:57], v[0:1] op_sel_hi:[1,1,0]
	v_lshlrev_b64 v[176:177], 11, v[176:177]
	v_mov_b32_e32 v207, v208
	v_pk_add_f32 v[204:205], v[204:205], v[206:207]
	s_waitcnt vmcnt(3)
	v_mov_b32_e32 v220, v178
	v_pk_add_f32 v[202:203], v[202:203], v[204:205]
	s_waitcnt vmcnt(2)
	v_mov_b32_e32 v221, v190
	v_add_f32_e32 v0, v202, v203
	v_ffbh_u32_e32 v203, v175
	v_min_u32_e32 v203, 32, v203
	v_lshlrev_b64 v[174:175], v203, v[174:175]
	ds_bpermute_b32 v202, v188, v0
	v_min_u32_e32 v174, 1, v174
	v_or_b32_e32 v174, v175, v174
	v_cvt_f32_u32_e32 v174, v174
	v_mov_b32_e32 v190, v179
	s_waitcnt lgkmcnt(0)
	v_add_f32_e32 v0, v0, v202
	v_sub_u32_e32 v202, 32, v203
	v_ldexp_f32 v174, v174, v202
	v_mov_b32_e32 v175, v0
	s_nop 1
	v_permlane32_swap_b32_e32 v175, v0
	v_fmamk_f32 v174, v174, 0x30800000, v240
	v_rsq_f32_e32 v202, v174
	s_waitcnt lgkmcnt(0)
	v_add_f32_e32 v0, v0, v175
	v_mul_f32_e32 v174, v202, v202
	v_mul_f32_e32 v0, v174, v0
	v_fmamk_f32 v0, v0, 0x3c800000, v240
	v_rsq_f32_e32 v0, v0
	v_add_u32_e32 v174, 0x90, v148
	v_ashrrev_i32_e32 v175, 31, v174
	v_mul_f32_e32 v0, v202, v0
	v_pk_mul_f32 v[202:203], v[62:63], v[0:1] op_sel_hi:[1,0]
	v_pk_mul_f32 v[204:205], v[64:65], v[0:1] op_sel_hi:[1,0]
	v_pk_mul_f32 v[202:203], v[162:163], v[202:203]
	ds_bpermute_b32 v218, v188, v202
	v_pk_mul_f32 v[206:207], v[58:59], v[0:1] op_sel_hi:[1,0]
	v_pk_mul_f32 v[208:209], v[60:61], v[0:1] op_sel_hi:[1,0]
	v_pk_mul_f32 v[210:211], v[54:55], v[0:1] op_sel_hi:[1,0]
	v_pk_mul_f32 v[212:213], v[56:57], v[0:1] op_sel_hi:[1,0]
	v_pk_mul_f32 v[214:215], v[50:51], v[0:1] op_sel_hi:[1,0]
	v_pk_mul_f32 v[216:217], v[52:53], v[0:1] op_sel_hi:[1,0]
	ds_bpermute_b32 v0, v188, v203
	s_waitcnt lgkmcnt(1)
; __device__ __forceinline__ unsigned cvt_pk_bf16(float lo, float hi) { unsigned r; asm volatile("v_cvt_pk_bf16_f32 %0, %1, %2" : "=v"(r) : "v"(lo), "v"(hi)); return r; }
;     __device__ __forceinline__ void operator()(const f32x4 (&acc)[2][2][4][2], const Unit& u, int wr, int wc, int fr, int fq) const {
;     ...
;                 ss += __shfl_xor(ss, 16); ss += __shfl_xor(ss, 32);
;                 const float rs = __builtin_amdgcn_rsqf((float)sq[ai][m] * (1.0f / (1024.0f * 1048576.0f)) + RMS_EPS);
;                 const float rn = rs * __builtin_amdgcn_rsqf(rs * rs * ss * (1.0f / 64.0f) + RMS_EPS);
; #pragma unroll
;                 for (int bj = 0; bj < 2; ++bj)
; #pragma unroll
;                     for (int n = 0; n < 2; ++n) v[bj][n] = v[bj][n] * rn * g[bj][n];
;                 const f32x4 c0 = *(const f32x4*)(cs + (size_t)row * 8), c1 = *(const f32x4*)(cs + (size_t)row * 8 + 4), s0 = *(const f32x4*)(sn + (size_t)row * 8), s1 = *(const f32x4*)(sn + (size_t)row * 8 + 4);
; #pragma unroll
;                 for (int n = 0; n < 2; ++n)
; #pragma unroll
;                     for (int j = 0; j < 4; ++j) { const float own = v[0][n][j], oth = __shfl_xor(own, 16); const float c = n ? c1[j] : c0[j], s = n ? s1[j] : s0[j];
;                         v[0][n][j] = rot ? (own * c + sgn * oth * s) : own; }
;                 bf16_t* rowp = base + (size_t)row * 1024 + col0;
; #pragma unroll
;                 for (int bj = 0; bj < 2; ++bj) { u32x4 w; w.x = cvt_pk_bf16(v[bj][0][0], v[bj][0][1]); w.y = cvt_pk_bf16(v[bj][0][2], v[bj][0][3]); w.z = cvt_pk_bf16(v[bj][1][0], v[bj][1][1]); w.w = cvt_pk_bf16(v[bj][1][2], v[bj][1][3]);
;                     *(u32x4*)(rowp + 32 * bj) = w; } }
	v_cndmask_b32_e64 v218, v218, -v218, s[0:1]
	v_mov_b32_e32 v219, v202
	v_pk_mul_f32 v[218:219], v[220:221], v[218:219]
	v_pk_mul_f32 v[204:205], v[160:161], v[204:205]
	v_add_f32_e32 v178, v218, v219
	v_cndmask_b32_e64 v218, v202, v178, s[4:5]
	s_waitcnt lgkmcnt(0)
	v_cndmask_b32_e64 v202, v0, -v0, s[0:1]
	ds_bpermute_b32 v0, v188, v204
	v_pk_mul_f32 v[178:179], v[190:191], v[202:203]
	v_mov_b32_e32 v190, v180
	v_add_f32_e32 v178, v178, v179
	v_cndmask_b32_e64 v202, v203, v178, s[4:5]
	s_waitcnt lgkmcnt(0)
	v_cndmask_b32_e64 v178, v0, -v0, s[0:1]
	ds_bpermute_b32 v0, v188, v205
	v_mov_b32_e32 v191, v192
	v_mov_b32_e32 v179, v204
	v_pk_mul_f32 v[178:179], v[190:191], v[178:179]
	v_pk_mul_f32 v[206:207], v[166:167], v[206:207]
	v_add_f32_e32 v178, v178, v179
	v_cndmask_b32_e64 v203, v204, v178, s[4:5]
	s_waitcnt lgkmcnt(0)
	v_cndmask_b32_e64 v204, v0, -v0, s[0:1]
	ds_bpermute_b32 v0, v188, v206
	v_mov_b32_e32 v192, v181
	v_pk_mul_f32 v[178:179], v[192:193], v[204:205]
	v_pk_mul_f32 v[208:209], v[164:165], v[208:209]
	v_add_f32_e32 v178, v178, v179
	v_cndmask_b32_e64 v192, v205, v178, s[4:5]
	s_waitcnt lgkmcnt(0)
	v_cndmask_b32_e64 v178, v0, -v0, s[0:1]
	ds_bpermute_b32 v0, v188, v207
	v_pk_mov_b32 v[190:191], v[208:209], v[206:207] op_sel:[1,0]
	s_waitcnt vmcnt(0)
	v_mov_b32_e32 v180, v198
	v_mov_b32_e32 v181, v194
	v_mov_b32_e32 v179, v191
	v_pk_mul_f32 v[178:179], v[180:181], v[178:179]
	v_mov_b32_e32 v194, v199
	v_add_f32_e32 v178, v178, v179
	v_cndmask_b32_e64 v193, v206, v178, s[4:5]
	s_waitcnt lgkmcnt(0)
	v_cndmask_b32_e64 v206, v0, -v0, s[0:1]
	ds_bpermute_b32 v0, v188, v208
	v_pk_mul_f32 v[178:179], v[194:195], v[206:207]
	v_mov_b32_e32 v180, v200
	v_add_f32_e32 v178, v178, v179
	v_cndmask_b32_e64 v194, v207, v178, s[4:5]
	s_waitcnt lgkmcnt(0)
	v_cndmask_b32_e64 v178, v0, -v0, s[0:1]
	ds_bpermute_b32 v0, v188, v209
	v_mov_b32_e32 v181, v196
	v_mov_b32_e32 v179, v208
	v_pk_mul_f32 v[178:179], v[180:181], v[178:179]
	v_mov_b32_e32 v200, v197
	v_add_f32_e32 v178, v178, v179
	s_waitcnt lgkmcnt(0)
	v_cndmask_b32_e64 v191, v0, -v0, s[0:1]
	v_cndmask_b32_e64 v195, v208, v178, s[4:5]
	v_pk_mul_f32 v[178:179], v[200:201], v[190:191]
	v_lshl_add_u64 v[180:181], v[150:151], 0, v[176:177]
	v_add_f32_e32 v0, v178, v179
	v_cvt_pk_bf16_f32 v176, v218, v202
	v_cvt_pk_bf16_f32 v177, v203, v192
	v_pk_mul_f32 v[212:213], v[154:155], v[212:213]
	v_pk_mul_f32 v[210:211], v[168:169], v[210:211]
	v_cndmask_b32_e64 v0, v209, v0, s[4:5]
	v_cvt_pk_bf16_f32 v178, v193, v194
	v_cvt_pk_bf16_f32 v179, v195, v0
	global_store_dwordx4 v[180:181], v[176:179], off
	v_pk_mul_f32 v[216:217], v[156:157], v[216:217]
	v_pk_mul_f32 v[214:215], v[158:159], v[214:215]
	v_cvt_pk_bf16_f32 v176, v210, v211
	v_cvt_pk_bf16_f32 v177, v212, v213
	v_pk_mul_f32 v[202:203], v[46:47], v[46:47]
	v_cvt_pk_bf16_f32 v178, v214, v215
	v_cvt_pk_bf16_f32 v179, v216, v217
	global_store_dwordx4 v[180:181], v[176:179], off offset:64
	v_mul_f32_e32 v0, v34, v34
	s_nop 0
	v_lshlrev_b64 v[176:177], 5, v[174:175]
	v_lshl_add_u64 v[198:199], s[26:27], 0, v[176:177]
	v_lshl_add_u64 v[180:181], s[24:25], 0, v[176:177]
	global_load_dwordx4 v[176:179], v[198:199], off
	global_load_dwordx4 v[190:193], v[180:181], off
	global_load_dwordx4 v[194:197], v[180:181], off offset:16
	s_nop 0
	global_load_dwordx4 v[198:201], v[198:199], off offset:16
	v_pk_mul_f32 v[180:181], v[48:49], v[48:49]
	v_lshlrev_b64 v[174:175], 11, v[174:175]
	v_pk_mov_b32 v[204:205], v[202:203], v[180:181] op_sel:[1,0]
	v_mov_b32_e32 v203, v181
	v_pk_add_f32 v[180:181], v[204:205], v[202:203]
	v_pk_mul_f32 v[202:203], v[44:45], v[44:45]
	v_pk_mul_f32 v[204:205], v[42:43], v[42:43]
	v_pk_add_f32 v[180:181], v[180:181], v[180:181] op_sel:[0,1] op_sel_hi:[1,0]
	v_pk_mov_b32 v[206:207], v[204:205], v[202:203] op_sel:[1,0]
	v_mov_b32_e32 v205, v203
	v_pk_add_f32 v[202:203], v[206:207], v[204:205]
	v_mul_f32_e32 v204, v35, v35
	v_pk_add_f32 v[202:203], v[202:203], v[202:203] op_sel:[0,1] op_sel_hi:[1,0]
	v_mov_b32_e32 v181, v0
	v_mov_b32_e32 v203, v204
	v_mul_f32_e32 v0, v39, v39
	v_mul_f32_e32 v205, v36, v36
	v_pk_add_f32 v[180:181], v[180:181], v[202:203]
	v_pk_fma_f32 v[202:203], v[38:39], v[38:39], v[0:1] op_sel_hi:[1,1,0]
	v_mul_f32_e32 v0, v41, v41
	v_mul_f32_e32 v206, v37, v37
	v_mov_b32_e32 v203, v205
	v_pk_fma_f32 v[204:205], v[40:41], v[40:41], v[0:1] op_sel_hi:[1,1,0]
	s_waitcnt vmcnt(3)
	v_mov_b32_e32 v218, v176
	v_mov_b32_e32 v205, v206
	v_pk_add_f32 v[202:203], v[202:203], v[204:205]
	s_waitcnt vmcnt(2)
	v_mov_b32_e32 v219, v190
	v_pk_add_f32 v[180:181], v[180:181], v[202:203]
	v_mov_b32_e32 v190, v177
	v_add_f32_e32 v0, v180, v181
	v_ffbh_u32_e32 v181, v173
	v_min_u32_e32 v181, 32, v181
	v_lshlrev_b64 v[172:173], v181, v[172:173]
	ds_bpermute_b32 v180, v188, v0
	v_min_u32_e32 v172, 1, v172
	v_or_b32_e32 v172, v173, v172
	v_cvt_f32_u32_e32 v172, v172
	s_waitcnt lgkmcnt(0)
	v_add_f32_e32 v0, v0, v180
	v_sub_u32_e32 v180, 32, v181
	v_ldexp_f32 v172, v172, v180
	v_mov_b32_e32 v173, v0
	s_nop 1
	v_permlane32_swap_b32_e32 v173, v0
	v_fmamk_f32 v172, v172, 0x30800000, v240
	v_rsq_f32_e32 v180, v172
	s_waitcnt lgkmcnt(0)
	v_add_f32_e32 v0, v0, v173
	v_mul_f32_e32 v172, v180, v180
	v_mul_f32_e32 v0, v172, v0
	v_fmamk_f32 v0, v0, 0x3c800000, v240
	v_rsq_f32_e32 v0, v0
	v_add_u32_e32 v172, 0xa0, v148
	v_ashrrev_i32_e32 v173, 31, v172
	v_mul_f32_e32 v0, v180, v0
	v_pk_mul_f32 v[180:181], v[46:47], v[0:1] op_sel_hi:[1,0]
	v_pk_mul_f32 v[202:203], v[48:49], v[0:1] op_sel_hi:[1,0]
	v_pk_mul_f32 v[180:181], v[162:163], v[180:181]
	ds_bpermute_b32 v216, v188, v180
	v_pk_mul_f32 v[204:205], v[42:43], v[0:1] op_sel_hi:[1,0]
	v_pk_mul_f32 v[206:207], v[44:45], v[0:1] op_sel_hi:[1,0]
	v_pk_mul_f32 v[208:209], v[38:39], v[0:1] op_sel_hi:[1,0]
	v_pk_mul_f32 v[210:211], v[40:41], v[0:1] op_sel_hi:[1,0]
	v_pk_mul_f32 v[212:213], v[34:35], v[0:1] op_sel_hi:[1,0]
	v_pk_mul_f32 v[214:215], v[36:37], v[0:1] op_sel_hi:[1,0]
	ds_bpermute_b32 v0, v188, v181
	s_waitcnt lgkmcnt(1)
; __device__ __forceinline__ unsigned cvt_pk_bf16(float lo, float hi) { unsigned r; asm volatile("v_cvt_pk_bf16_f32 %0, %1, %2" : "=v"(r) : "v"(lo), "v"(hi)); return r; }
;     __device__ __forceinline__ void operator()(const f32x4 (&acc)[2][2][4][2], const Unit& u, int wr, int wc, int fr, int fq) const {
;     ...
;                 ss += __shfl_xor(ss, 16); ss += __shfl_xor(ss, 32);
;                 const float rs = __builtin_amdgcn_rsqf((float)sq[ai][m] * (1.0f / (1024.0f * 1048576.0f)) + RMS_EPS);
;                 const float rn = rs * __builtin_amdgcn_rsqf(rs * rs * ss * (1.0f / 64.0f) + RMS_EPS);
; #pragma unroll
;                 for (int bj = 0; bj < 2; ++bj)
; #pragma unroll
;                     for (int n = 0; n < 2; ++n) v[bj][n] = v[bj][n] * rn * g[bj][n];
;                 const f32x4 c0 = *(const f32x4*)(cs + (size_t)row * 8), c1 = *(const f32x4*)(cs + (size_t)row * 8 + 4), s0 = *(const f32x4*)(sn + (size_t)row * 8), s1 = *(const f32x4*)(sn + (size_t)row * 8 + 4);
; #pragma unroll
;                 for (int n = 0; n < 2; ++n)
; #pragma unroll
;                     for (int j = 0; j < 4; ++j) { const float own = v[0][n][j], oth = __shfl_xor(own, 16); const float c = n ? c1[j] : c0[j], s = n ? s1[j] : s0[j];
;                         v[0][n][j] = rot ? (own * c + sgn * oth * s) : own; }
;                 bf16_t* rowp = base + (size_t)row * 1024 + col0;
; #pragma unroll
;                 for (int bj = 0; bj < 2; ++bj) { u32x4 w; w.x = cvt_pk_bf16(v[bj][0][0], v[bj][0][1]); w.y = cvt_pk_bf16(v[bj][0][2], v[bj][0][3]); w.z = cvt_pk_bf16(v[bj][1][0], v[bj][1][1]); w.w = cvt_pk_bf16(v[bj][1][2], v[bj][1][3]);
;                     *(u32x4*)(rowp + 32 * bj) = w; } }
	v_cndmask_b32_e64 v216, v216, -v216, s[0:1]
	v_mov_b32_e32 v217, v180
	v_pk_mul_f32 v[216:217], v[218:219], v[216:217]
	v_pk_mul_f32 v[202:203], v[160:161], v[202:203]
	v_add_f32_e32 v176, v216, v217
	v_cndmask_b32_e64 v216, v180, v176, s[4:5]
	s_waitcnt lgkmcnt(0)
	v_cndmask_b32_e64 v180, v0, -v0, s[0:1]
	ds_bpermute_b32 v0, v188, v202
	v_pk_mul_f32 v[176:177], v[190:191], v[180:181]
	v_mov_b32_e32 v180, v178
	v_add_f32_e32 v176, v176, v177
	v_cndmask_b32_e64 v190, v181, v176, s[4:5]
	s_waitcnt lgkmcnt(0)
	v_cndmask_b32_e64 v176, v0, -v0, s[0:1]
	ds_bpermute_b32 v0, v188, v203
	v_mov_b32_e32 v181, v192
	v_mov_b32_e32 v177, v202
	v_pk_mul_f32 v[176:177], v[180:181], v[176:177]
	v_pk_mul_f32 v[204:205], v[166:167], v[204:205]
	v_add_f32_e32 v176, v176, v177
	v_cndmask_b32_e64 v191, v202, v176, s[4:5]
	s_waitcnt lgkmcnt(0)
	v_cndmask_b32_e64 v202, v0, -v0, s[0:1]
	ds_bpermute_b32 v0, v188, v204
	v_mov_b32_e32 v192, v179
	v_pk_mul_f32 v[176:177], v[192:193], v[202:203]
	v_pk_mul_f32 v[206:207], v[164:165], v[206:207]
	v_add_f32_e32 v176, v176, v177
	v_cndmask_b32_e64 v192, v203, v176, s[4:5]
	s_waitcnt lgkmcnt(0)
	v_cndmask_b32_e64 v176, v0, -v0, s[0:1]
	ds_bpermute_b32 v0, v188, v205
	v_pk_mov_b32 v[180:181], v[206:207], v[204:205] op_sel:[1,0]
	s_waitcnt vmcnt(0)
	v_mov_b32_e32 v178, v198
	v_mov_b32_e32 v179, v194
	v_mov_b32_e32 v177, v181
	v_pk_mul_f32 v[176:177], v[178:179], v[176:177]
	v_mov_b32_e32 v194, v199
	v_add_f32_e32 v176, v176, v177
	v_cndmask_b32_e64 v193, v204, v176, s[4:5]
	s_waitcnt lgkmcnt(0)
	v_cndmask_b32_e64 v204, v0, -v0, s[0:1]
	ds_bpermute_b32 v0, v188, v206
	v_pk_mul_f32 v[176:177], v[194:195], v[204:205]
	v_mov_b32_e32 v178, v200
	v_add_f32_e32 v176, v176, v177
	v_cndmask_b32_e64 v194, v205, v176, s[4:5]
	s_waitcnt lgkmcnt(0)
	v_cndmask_b32_e64 v176, v0, -v0, s[0:1]
	ds_bpermute_b32 v0, v188, v207
	v_mov_b32_e32 v179, v196
	v_mov_b32_e32 v177, v206
	v_pk_mul_f32 v[176:177], v[178:179], v[176:177]
	v_mov_b32_e32 v200, v197
	v_add_f32_e32 v176, v176, v177
	s_waitcnt lgkmcnt(0)
	v_cndmask_b32_e64 v181, v0, -v0, s[0:1]
	v_cndmask_b32_e64 v195, v206, v176, s[4:5]
	v_pk_mul_f32 v[176:177], v[200:201], v[180:181]
	v_lshl_add_u64 v[178:179], v[150:151], 0, v[174:175]
	v_add_f32_e32 v0, v176, v177
	v_cvt_pk_bf16_f32 v174, v216, v190
	v_cvt_pk_bf16_f32 v175, v191, v192
	v_pk_mul_f32 v[210:211], v[154:155], v[210:211]
	v_pk_mul_f32 v[208:209], v[168:169], v[208:209]
	v_cndmask_b32_e64 v0, v207, v0, s[4:5]
	v_cvt_pk_bf16_f32 v176, v193, v194
	v_cvt_pk_bf16_f32 v177, v195, v0
	global_store_dwordx4 v[178:179], v[174:177], off
	v_pk_mul_f32 v[214:215], v[156:157], v[214:215]
	v_pk_mul_f32 v[212:213], v[158:159], v[212:213]
	v_cvt_pk_bf16_f32 v174, v208, v209
	v_cvt_pk_bf16_f32 v175, v210, v211
	v_pk_mul_f32 v[198:199], v[32:33], v[32:33]
	v_cvt_pk_bf16_f32 v176, v212, v213
	v_cvt_pk_bf16_f32 v177, v214, v215
	global_store_dwordx4 v[178:179], v[174:177], off offset:64
	v_pk_mul_f32 v[200:201], v[30:31], v[30:31]
	v_mul_f32_e32 v0, v18, v18
	v_lshlrev_b64 v[174:175], 5, v[172:173]
	v_lshl_add_u64 v[190:191], s[24:25], 0, v[174:175]
	v_lshl_add_u64 v[194:195], s[26:27], 0, v[174:175]
	global_load_dwordx4 v[174:177], v[194:195], off
	global_load_dwordx4 v[178:181], v[190:191], off
	s_nop 0
	global_load_dwordx4 v[190:193], v[190:191], off offset:16
	s_nop 0
	global_load_dwordx4 v[194:197], v[194:195], off offset:16
	v_pk_mov_b32 v[202:203], v[200:201], v[198:199] op_sel:[1,0]
	v_mov_b32_e32 v201, v199
	v_pk_add_f32 v[198:199], v[202:203], v[200:201]
	v_pk_mul_f32 v[200:201], v[28:29], v[28:29]
	v_pk_mul_f32 v[202:203], v[26:27], v[26:27]
	v_pk_add_f32 v[198:199], v[198:199], v[198:199] op_sel:[0,1] op_sel_hi:[1,0]
	v_pk_mov_b32 v[204:205], v[202:203], v[200:201] op_sel:[1,0]
	v_mov_b32_e32 v203, v201
	v_pk_add_f32 v[200:201], v[204:205], v[202:203]
	v_mul_f32_e32 v202, v19, v19
	v_pk_add_f32 v[200:201], v[200:201], v[200:201] op_sel:[0,1] op_sel_hi:[1,0]
	v_mov_b32_e32 v199, v0
	v_mov_b32_e32 v201, v202
	v_mul_f32_e32 v0, v23, v23
	v_mul_f32_e32 v203, v20, v20
	v_pk_add_f32 v[198:199], v[198:199], v[200:201]
	v_pk_fma_f32 v[200:201], v[22:23], v[22:23], v[0:1] op_sel_hi:[1,1,0]
	v_mul_f32_e32 v0, v25, v25
	v_mul_f32_e32 v204, v21, v21
	v_mov_b32_e32 v201, v203
	v_pk_fma_f32 v[202:203], v[24:25], v[24:25], v[0:1] op_sel_hi:[1,1,0]
	v_lshlrev_b64 v[172:173], 11, v[172:173]
	v_mov_b32_e32 v203, v204
	v_pk_add_f32 v[200:201], v[200:201], v[202:203]
	s_waitcnt vmcnt(3)
	v_mov_b32_e32 v216, v174
	v_pk_add_f32 v[198:199], v[198:199], v[200:201]
	s_waitcnt vmcnt(2)
	v_mov_b32_e32 v217, v178
	v_add_f32_e32 v0, v198, v199
	v_ffbh_u32_e32 v199, v171
	v_min_u32_e32 v199, 32, v199
	v_lshlrev_b64 v[170:171], v199, v[170:171]
	ds_bpermute_b32 v198, v188, v0
	v_min_u32_e32 v170, 1, v170
	v_or_b32_e32 v170, v171, v170
	v_cvt_f32_u32_e32 v170, v170
	v_mov_b32_e32 v178, v175
	s_waitcnt lgkmcnt(0)
	v_add_f32_e32 v0, v0, v198
	v_sub_u32_e32 v198, 32, v199
	v_ldexp_f32 v170, v170, v198
	v_mov_b32_e32 v171, v0
	s_nop 1
	v_permlane32_swap_b32_e32 v171, v0
	v_fmamk_f32 v170, v170, 0x30800000, v240
	v_rsq_f32_e32 v198, v170
	s_waitcnt lgkmcnt(0)
	v_add_f32_e32 v0, v0, v171
	v_mul_f32_e32 v170, v198, v198
	v_mul_f32_e32 v0, v170, v0
	v_fmamk_f32 v0, v0, 0x3c800000, v240
	v_rsq_f32_e32 v0, v0
	v_add_u32_e32 v170, 0xb0, v148
	v_ashrrev_i32_e32 v171, 31, v170
	v_mul_f32_e32 v0, v198, v0
	v_pk_mul_f32 v[198:199], v[30:31], v[0:1] op_sel_hi:[1,0]
	v_pk_mul_f32 v[200:201], v[32:33], v[0:1] op_sel_hi:[1,0]
	v_pk_mul_f32 v[198:199], v[162:163], v[198:199]
	ds_bpermute_b32 v214, v188, v198
	v_pk_mul_f32 v[202:203], v[26:27], v[0:1] op_sel_hi:[1,0]
	v_pk_mul_f32 v[204:205], v[28:29], v[0:1] op_sel_hi:[1,0]
	v_pk_mul_f32 v[206:207], v[22:23], v[0:1] op_sel_hi:[1,0]
	v_pk_mul_f32 v[208:209], v[24:25], v[0:1] op_sel_hi:[1,0]
	v_pk_mul_f32 v[210:211], v[18:19], v[0:1] op_sel_hi:[1,0]
	v_pk_mul_f32 v[212:213], v[20:21], v[0:1] op_sel_hi:[1,0]
	ds_bpermute_b32 v0, v188, v199
	s_waitcnt lgkmcnt(1)
; __device__ __forceinline__ unsigned cvt_pk_bf16(float lo, float hi) { unsigned r; asm volatile("v_cvt_pk_bf16_f32 %0, %1, %2" : "=v"(r) : "v"(lo), "v"(hi)); return r; }
;     __device__ __forceinline__ void operator()(const f32x4 (&acc)[2][2][4][2], const Unit& u, int wr, int wc, int fr, int fq) const {
;     ...
;                 ss += __shfl_xor(ss, 16); ss += __shfl_xor(ss, 32);
;                 const float rs = __builtin_amdgcn_rsqf((float)sq[ai][m] * (1.0f / (1024.0f * 1048576.0f)) + RMS_EPS);
;                 const float rn = rs * __builtin_amdgcn_rsqf(rs * rs * ss * (1.0f / 64.0f) + RMS_EPS);
; #pragma unroll
;                 for (int bj = 0; bj < 2; ++bj)
; #pragma unroll
;                     for (int n = 0; n < 2; ++n) v[bj][n] = v[bj][n] * rn * g[bj][n];
;                 const f32x4 c0 = *(const f32x4*)(cs + (size_t)row * 8), c1 = *(const f32x4*)(cs + (size_t)row * 8 + 4), s0 = *(const f32x4*)(sn + (size_t)row * 8), s1 = *(const f32x4*)(sn + (size_t)row * 8 + 4);
; #pragma unroll
;                 for (int n = 0; n < 2; ++n)
; #pragma unroll
;                     for (int j = 0; j < 4; ++j) { const float own = v[0][n][j], oth = __shfl_xor(own, 16); const float c = n ? c1[j] : c0[j], s = n ? s1[j] : s0[j];
;                         v[0][n][j] = rot ? (own * c + sgn * oth * s) : own; }
;                 bf16_t* rowp = base + (size_t)row * 1024 + col0;
; #pragma unroll
;                 for (int bj = 0; bj < 2; ++bj) { u32x4 w; w.x = cvt_pk_bf16(v[bj][0][0], v[bj][0][1]); w.y = cvt_pk_bf16(v[bj][0][2], v[bj][0][3]); w.z = cvt_pk_bf16(v[bj][1][0], v[bj][1][1]); w.w = cvt_pk_bf16(v[bj][1][2], v[bj][1][3]);
;                     *(u32x4*)(rowp + 32 * bj) = w; } }
	v_cndmask_b32_e64 v214, v214, -v214, s[0:1]
	v_mov_b32_e32 v215, v198
	v_pk_mul_f32 v[214:215], v[216:217], v[214:215]
	v_pk_mul_f32 v[200:201], v[160:161], v[200:201]
	v_add_f32_e32 v174, v214, v215
	v_cndmask_b32_e64 v214, v198, v174, s[4:5]
	s_waitcnt lgkmcnt(0)
	v_cndmask_b32_e64 v198, v0, -v0, s[0:1]
	ds_bpermute_b32 v0, v188, v200
	v_pk_mul_f32 v[174:175], v[178:179], v[198:199]
	v_mov_b32_e32 v178, v176
	v_add_f32_e32 v174, v174, v175
	v_cndmask_b32_e64 v198, v199, v174, s[4:5]
	s_waitcnt lgkmcnt(0)
	v_cndmask_b32_e64 v174, v0, -v0, s[0:1]
	ds_bpermute_b32 v0, v188, v201
	v_mov_b32_e32 v179, v180
	v_mov_b32_e32 v175, v200
	v_pk_mul_f32 v[174:175], v[178:179], v[174:175]
	v_pk_mul_f32 v[202:203], v[166:167], v[202:203]
	v_add_f32_e32 v174, v174, v175
	v_cndmask_b32_e64 v199, v200, v174, s[4:5]
	s_waitcnt lgkmcnt(0)
	v_cndmask_b32_e64 v200, v0, -v0, s[0:1]
	ds_bpermute_b32 v0, v188, v202
	v_mov_b32_e32 v180, v177
	v_pk_mul_f32 v[174:175], v[180:181], v[200:201]
	v_pk_mul_f32 v[204:205], v[164:165], v[204:205]
	v_add_f32_e32 v174, v174, v175
	v_cndmask_b32_e64 v180, v201, v174, s[4:5]
	s_waitcnt lgkmcnt(0)
	v_cndmask_b32_e64 v174, v0, -v0, s[0:1]
	ds_bpermute_b32 v0, v188, v203
	v_pk_mov_b32 v[178:179], v[204:205], v[202:203] op_sel:[1,0]
	s_waitcnt vmcnt(0)
	v_mov_b32_e32 v176, v194
	v_mov_b32_e32 v177, v190
	v_mov_b32_e32 v175, v179
	v_pk_mul_f32 v[174:175], v[176:177], v[174:175]
	v_mov_b32_e32 v190, v195
	v_add_f32_e32 v174, v174, v175
	v_cndmask_b32_e64 v181, v202, v174, s[4:5]
	s_waitcnt lgkmcnt(0)
	v_cndmask_b32_e64 v202, v0, -v0, s[0:1]
	ds_bpermute_b32 v0, v188, v204
	v_pk_mul_f32 v[174:175], v[190:191], v[202:203]
	v_mov_b32_e32 v176, v196
	v_add_f32_e32 v174, v174, v175
	v_cndmask_b32_e64 v190, v203, v174, s[4:5]
	s_waitcnt lgkmcnt(0)
	v_cndmask_b32_e64 v174, v0, -v0, s[0:1]
	ds_bpermute_b32 v0, v188, v205
	v_mov_b32_e32 v177, v192
	v_mov_b32_e32 v175, v204
	v_pk_mul_f32 v[174:175], v[176:177], v[174:175]
	v_mov_b32_e32 v196, v193
	v_add_f32_e32 v174, v174, v175
	s_waitcnt lgkmcnt(0)
	v_cndmask_b32_e64 v179, v0, -v0, s[0:1]
	v_cndmask_b32_e64 v191, v204, v174, s[4:5]
	v_pk_mul_f32 v[174:175], v[196:197], v[178:179]
	v_lshl_add_u64 v[176:177], v[150:151], 0, v[172:173]
	v_add_f32_e32 v0, v174, v175
	v_cvt_pk_bf16_f32 v172, v214, v198
	v_cvt_pk_bf16_f32 v173, v199, v180
	v_pk_mul_f32 v[208:209], v[154:155], v[208:209]
	v_pk_mul_f32 v[206:207], v[168:169], v[206:207]
	v_cndmask_b32_e64 v0, v205, v0, s[4:5]
	v_cvt_pk_bf16_f32 v174, v181, v190
	v_cvt_pk_bf16_f32 v175, v191, v0
	global_store_dwordx4 v[176:177], v[172:175], off
	v_pk_mul_f32 v[212:213], v[156:157], v[212:213]
	v_pk_mul_f32 v[210:211], v[158:159], v[210:211]
	v_cvt_pk_bf16_f32 v172, v206, v207
	v_cvt_pk_bf16_f32 v173, v208, v209
	v_pk_mul_f32 v[198:199], v[14:15], v[14:15]
	v_cvt_pk_bf16_f32 v174, v210, v211
	v_cvt_pk_bf16_f32 v175, v212, v213
	global_store_dwordx4 v[176:177], v[172:175], off offset:64
	v_mul_f32_e32 v0, v2, v2
	s_nop 0
	v_lshlrev_b64 v[172:173], 5, v[170:171]
	v_lshl_add_u64 v[194:195], s[26:27], 0, v[172:173]
	v_lshl_add_u64 v[180:181], s[24:25], 0, v[172:173]
	global_load_dwordx4 v[172:175], v[194:195], off
	global_load_dwordx4 v[176:179], v[180:181], off
	global_load_dwordx4 v[190:193], v[180:181], off offset:16
	s_nop 0
	global_load_dwordx4 v[194:197], v[194:195], off offset:16
	v_pk_mul_f32 v[180:181], v[16:17], v[16:17]
	s_nop 0
	v_pk_mov_b32 v[200:201], v[198:199], v[180:181] op_sel:[1,0]
	v_mov_b32_e32 v199, v181
	v_pk_add_f32 v[180:181], v[200:201], v[198:199]
	v_pk_mul_f32 v[198:199], v[12:13], v[12:13]
	v_pk_mul_f32 v[200:201], v[10:11], v[10:11]
	v_pk_add_f32 v[180:181], v[180:181], v[180:181] op_sel:[0,1] op_sel_hi:[1,0]
	v_pk_mov_b32 v[202:203], v[200:201], v[198:199] op_sel:[1,0]
	v_mov_b32_e32 v201, v199
	v_pk_add_f32 v[198:199], v[202:203], v[200:201]
	v_mul_f32_e32 v200, v3, v3
	v_pk_add_f32 v[198:199], v[198:199], v[198:199] op_sel:[0,1] op_sel_hi:[1,0]
	v_mov_b32_e32 v181, v0
	v_mov_b32_e32 v199, v200
	v_mul_f32_e32 v0, v7, v7
	v_mul_f32_e32 v201, v4, v4
	v_pk_add_f32 v[180:181], v[180:181], v[198:199]
	v_pk_fma_f32 v[198:199], v[6:7], v[6:7], v[0:1] op_sel_hi:[1,1,0]
	v_mul_f32_e32 v0, v9, v9
	v_mul_f32_e32 v202, v5, v5
	v_mov_b32_e32 v199, v201
	v_pk_fma_f32 v[200:201], v[8:9], v[8:9], v[0:1] op_sel_hi:[1,1,0]
	s_nop 0
	v_mov_b32_e32 v201, v202
	v_pk_add_f32 v[198:199], v[198:199], v[200:201]
	s_nop 0
	v_pk_add_f32 v[180:181], v[180:181], v[198:199]
	s_nop 0
	v_add_f32_e32 v0, v180, v181
	v_ffbh_u32_e32 v181, v153
	v_min_u32_e32 v181, 32, v181
	v_lshlrev_b64 v[152:153], v181, v[152:153]
	ds_bpermute_b32 v180, v188, v0
	v_min_u32_e32 v152, 1, v152
	v_or_b32_e32 v152, v153, v152
	v_cvt_f32_u32_e32 v152, v152
	s_waitcnt lgkmcnt(0)
; __device__ __forceinline__ unsigned cvt_pk_bf16(float lo, float hi) { unsigned r; asm volatile("v_cvt_pk_bf16_f32 %0, %1, %2" : "=v"(r) : "v"(lo), "v"(hi)); return r; }
;     __device__ __forceinline__ void operator()(const f32x4 (&acc)[2][2][4][2], const Unit& u, int wr, int wc, int fr, int fq) const {
;     ...
;                 ss += __shfl_xor(ss, 16); ss += __shfl_xor(ss, 32);
;                 const float rs = __builtin_amdgcn_rsqf((float)sq[ai][m] * (1.0f / (1024.0f * 1048576.0f)) + RMS_EPS);
;                 const float rn = rs * __builtin_amdgcn_rsqf(rs * rs * ss * (1.0f / 64.0f) + RMS_EPS);
; #pragma unroll
;                 for (int bj = 0; bj < 2; ++bj)
; #pragma unroll
;                     for (int n = 0; n < 2; ++n) v[bj][n] = v[bj][n] * rn * g[bj][n];
;                 const f32x4 c0 = *(const f32x4*)(cs + (size_t)row * 8), c1 = *(const f32x4*)(cs + (size_t)row * 8 + 4), s0 = *(const f32x4*)(sn + (size_t)row * 8), s1 = *(const f32x4*)(sn + (size_t)row * 8 + 4);
; #pragma unroll
;                 for (int n = 0; n < 2; ++n)
; #pragma unroll
;                     for (int j = 0; j < 4; ++j) { const float own = v[0][n][j], oth = __shfl_xor(own, 16); const float c = n ? c1[j] : c0[j], s = n ? s1[j] : s0[j];
;                         v[0][n][j] = rot ? (own * c + sgn * oth * s) : own; }
;                 bf16_t* rowp = base + (size_t)row * 1024 + col0;
; #pragma unroll
;                 for (int bj = 0; bj < 2; ++bj) { u32x4 w; w.x = cvt_pk_bf16(v[bj][0][0], v[bj][0][1]); w.y = cvt_pk_bf16(v[bj][0][2], v[bj][0][3]); w.z = cvt_pk_bf16(v[bj][1][0], v[bj][1][1]); w.w = cvt_pk_bf16(v[bj][1][2], v[bj][1][3]);
;                     *(u32x4*)(rowp + 32 * bj) = w; } }
	v_add_f32_e32 v0, v0, v180
	v_sub_u32_e32 v180, 32, v181
	v_ldexp_f32 v152, v152, v180
	v_mov_b32_e32 v153, v0
	s_nop 1
	v_permlane32_swap_b32_e32 v153, v0
	v_fmamk_f32 v152, v152, 0x30800000, v240
	v_rsq_f32_e32 v152, v152
	s_waitcnt lgkmcnt(0)
	v_add_f32_e32 v0, v0, v153
	v_mul_f32_e32 v153, v152, v152
	v_mul_f32_e32 v0, v153, v0
	v_fmamk_f32 v0, v0, 0x3c800000, v240
	v_rsq_f32_e32 v0, v0
	s_nop 0
	v_mul_f32_e32 v0, v152, v0
	v_pk_mul_f32 v[152:153], v[14:15], v[0:1] op_sel_hi:[1,0]
	v_pk_mul_f32 v[180:181], v[16:17], v[0:1] op_sel_hi:[1,0]
	v_pk_mul_f32 v[152:153], v[162:163], v[152:153]
	ds_bpermute_b32 v189, v188, v152
	v_pk_mul_f32 v[160:161], v[160:161], v[180:181]
	v_pk_mul_f32 v[162:163], v[10:11], v[0:1] op_sel_hi:[1,0]
	v_pk_mul_f32 v[180:181], v[12:13], v[0:1] op_sel_hi:[1,0]
	v_pk_mul_f32 v[162:163], v[166:167], v[162:163]
	v_pk_mul_f32 v[164:165], v[164:165], v[180:181]
	v_pk_mul_f32 v[166:167], v[6:7], v[0:1] op_sel_hi:[1,0]
	v_pk_mul_f32 v[180:181], v[8:9], v[0:1] op_sel_hi:[1,0]
	v_pk_mul_f32 v[166:167], v[168:169], v[166:167]
	v_pk_mul_f32 v[154:155], v[154:155], v[180:181]
	v_pk_mul_f32 v[168:169], v[2:3], v[0:1] op_sel_hi:[1,0]
	v_pk_mul_f32 v[180:181], v[4:5], v[0:1] op_sel_hi:[1,0]
	ds_bpermute_b32 v0, v188, v153
	v_pk_mul_f32 v[156:157], v[156:157], v[180:181]
	v_pk_mul_f32 v[158:159], v[158:159], v[168:169]
	s_waitcnt lgkmcnt(1)
	v_cndmask_b32_e64 v168, v189, -v189, s[0:1]
	v_mov_b32_e32 v169, v152
	s_waitcnt vmcnt(3)
	v_mov_b32_e32 v180, v172
	s_waitcnt vmcnt(2)
	v_mov_b32_e32 v181, v176
	v_pk_mul_f32 v[168:169], v[180:181], v[168:169]
	v_mov_b32_e32 v176, v173
	v_add_f32_e32 v168, v168, v169
	v_cndmask_b32_e64 v172, v152, v168, s[4:5]
	s_waitcnt lgkmcnt(0)
	v_cndmask_b32_e64 v152, v0, -v0, s[0:1]
	ds_bpermute_b32 v0, v188, v160
	v_pk_mul_f32 v[168:169], v[176:177], v[152:153]
	s_nop 0
	v_add_f32_e32 v152, v168, v169
	v_cndmask_b32_e64 v173, v153, v152, s[4:5]
	s_waitcnt lgkmcnt(0)
	v_cndmask_b32_e64 v152, v0, -v0, s[0:1]
	ds_bpermute_b32 v0, v188, v161
	v_mov_b32_e32 v168, v174
	v_mov_b32_e32 v169, v178
	v_mov_b32_e32 v153, v160
	v_pk_mul_f32 v[152:153], v[168:169], v[152:153]
	v_mov_b32_e32 v178, v175
	v_add_f32_e32 v152, v152, v153
	v_cndmask_b32_e64 v174, v160, v152, s[4:5]
	s_waitcnt lgkmcnt(0)
	v_cndmask_b32_e64 v160, v0, -v0, s[0:1]
	ds_bpermute_b32 v0, v188, v162
	v_pk_mul_f32 v[152:153], v[178:179], v[160:161]
	v_pk_mov_b32 v[168:169], v[164:165], v[162:163] op_sel:[1,0]
	v_add_f32_e32 v152, v152, v153
	v_cndmask_b32_e64 v175, v161, v152, s[4:5]
	s_waitcnt lgkmcnt(0)
	v_cndmask_b32_e64 v152, v0, -v0, s[0:1]
	ds_bpermute_b32 v0, v188, v163
	s_waitcnt vmcnt(0)
	v_mov_b32_e32 v160, v194
	v_mov_b32_e32 v161, v190
	v_mov_b32_e32 v153, v169
	v_pk_mul_f32 v[152:153], v[160:161], v[152:153]
	v_mov_b32_e32 v190, v195
	v_add_f32_e32 v152, v152, v153
	v_cndmask_b32_e64 v176, v162, v152, s[4:5]
	s_waitcnt lgkmcnt(0)
	v_cndmask_b32_e64 v162, v0, -v0, s[0:1]
	ds_bpermute_b32 v0, v188, v164
	v_pk_mul_f32 v[152:153], v[190:191], v[162:163]
	v_mov_b32_e32 v160, v196
	v_add_f32_e32 v152, v152, v153
	v_cndmask_b32_e64 v162, v163, v152, s[4:5]
	s_waitcnt lgkmcnt(0)
	v_cndmask_b32_e64 v152, v0, -v0, s[0:1]
	ds_bpermute_b32 v0, v188, v165
	v_mov_b32_e32 v161, v192
	v_mov_b32_e32 v153, v164
	v_pk_mul_f32 v[152:153], v[160:161], v[152:153]
	v_mov_b32_e32 v196, v193
	v_add_f32_e32 v152, v152, v153
	s_waitcnt lgkmcnt(0)
	v_cndmask_b32_e64 v169, v0, -v0, s[0:1]
	v_cndmask_b32_e64 v163, v164, v152, s[4:5]
	v_pk_mul_f32 v[152:153], v[196:197], v[168:169]
	s_nop 0
	v_add_f32_e32 v0, v152, v153
	v_lshlrev_b64 v[152:153], 11, v[170:171]
	v_cndmask_b32_e64 v0, v165, v0, s[4:5]
	v_lshl_add_u64 v[160:161], v[150:151], 0, v[152:153]
	v_cvt_pk_bf16_f32 v150, v172, v173
	v_cvt_pk_bf16_f32 v151, v174, v175
	v_cvt_pk_bf16_f32 v152, v176, v162
	v_cvt_pk_bf16_f32 v153, v163, v0
	global_store_dwordx4 v[160:161], v[150:153], off
	s_nop 1
	v_cvt_pk_bf16_f32 v150, v166, v167
	v_cvt_pk_bf16_f32 v151, v154, v155
	v_cvt_pk_bf16_f32 v152, v158, v159
	v_cvt_pk_bf16_f32 v153, v156, v157
	global_store_dwordx4 v[160:161], v[150:153], off offset:64
	s_cbranch_execz .LBB0_141

; __device__ __forceinline__ unsigned cvt_pk_bf16(float lo, float hi) { unsigned r; asm volatile("v_cvt_pk_bf16_f32 %0, %1, %2" : "=v"(r) : "v"(lo), "v"(hi)); return r; }
;     __device__ __forceinline__ void operator()(const f32x4 (&acc)[2][2][4][2], const Unit& u, int wr, int wc, int fr, int fq) const {
;     ...
;         for (int ai = 0; ai < 2; ++ai) {
;             u32x4 raw[4][2];
; #pragma unroll
;             for (int m = 0; m < 4; ++m)
; #pragma unroll
;                 for (int bj = 0; bj < 2; ++bj) raw[m][bj] = *(const u32x4*)(xb + (size_t)(row0 + ai * HALF + m * 16) * 1024 + col0 + bj * HALF);
; #pragma unroll
;             for (int m = 0; m < 4; ++m) { const int row = row0 + ai * HALF + m * 16; const size_t off = (size_t)row * 1024 + col0; float s = 0.f;
; #pragma unroll
;                 for (int bj = 0; bj < 2; ++bj) { const u32x4 rw = raw[m][bj];
;                     f32x4 o0, o1;
;                     o0[0] = __uint_as_float(rw.x << 16) + acc[ai][bj][m][0][0]; o0[1] = __uint_as_float(rw.x & 0xffff0000u) + acc[ai][bj][m][0][1];
;                     o0[2] = __uint_as_float(rw.y << 16) + acc[ai][bj][m][0][2]; o0[3] = __uint_as_float(rw.y & 0xffff0000u) + acc[ai][bj][m][0][3];
;                     o1[0] = __uint_as_float(rw.z << 16) + acc[ai][bj][m][1][0]; o1[1] = __uint_as_float(rw.z & 0xffff0000u) + acc[ai][bj][m][1][1];
;                     o1[2] = __uint_as_float(rw.w << 16) + acc[ai][bj][m][1][2]; o1[3] = __uint_as_float(rw.w & 0xffff0000u) + acc[ai][bj][m][1][3];
;                     if (out) { *(f32x4*)(out + off + bj * HALF) = o0; *(f32x4*)(out + off + bj * HALF + 4) = o1; }
;                     else { u32x4 w; w.x = cvt_pk_bf16(o0[0], o0[1]); w.y = cvt_pk_bf16(o0[2], o0[3]); w.z = cvt_pk_bf16(o1[0], o1[1]); w.w = cvt_pk_bf16(o1[2], o1[3]); *(u32x4*)(xb + off + bj * HALF) = w;
;                         s += ((o0[0] * o0[0] + o0[1] * o0[1]) + (o0[2] * o0[2] + o0[3] * o0[3])) + ((o1[0] * o1[0] + o1[1] * o1[1]) + (o1[2] * o1[2] + o1[3] * o1[3])); } }
;                 if (!out) { s += __shfl_xor(s, 16); s += __shfl_xor(s, 32); if (fq == 0) atomicAdd(ssq_next + row, (unsigned long long)(s * 1048576.0f)); } }
.LBB0_353:
	v_lshl_or_b32 v164, s20, 8, v184
	v_lshl_add_u32 v168, s18, 8, v182
	v_ashrrev_i32_e32 v165, 31, v164
	v_readlane_b32 s18, v254, 15
	v_lshlrev_b64 v[194:195], 1, v[164:165]
	v_readlane_b32 s19, v254, 16
	v_ashrrev_i32_e32 v169, 31, v168
	v_lshlrev_b64 v[196:197], 11, v[168:169]
	v_lshl_add_u64 v[166:167], s[18:19], 0, v[194:195]
	v_lshl_add_u64 v[114:115], v[166:167], 0, v[196:197]
	global_load_dwordx4 v[186:189], v[114:115], off
	global_load_dwordx4 v[190:193], v[114:115], off offset:256
	v_or_b32_e32 v178, 16, v168
	v_ashrrev_i32_e32 v179, 31, v178
	v_or_b32_e32 v174, 32, v168
	v_lshlrev_b64 v[180:181], 11, v[178:179]
	v_ashrrev_i32_e32 v175, 31, v174
	v_or_b32_e32 v170, 48, v168
	v_lshl_add_u64 v[114:115], v[166:167], 0, v[180:181]
	v_lshlrev_b64 v[176:177], 11, v[174:175]
	v_ashrrev_i32_e32 v171, 31, v170
	global_load_dwordx4 v[134:137], v[114:115], off
	global_load_dwordx4 v[130:133], v[114:115], off offset:256
	v_lshl_add_u64 v[114:115], v[166:167], 0, v[176:177]
	v_lshlrev_b64 v[172:173], 11, v[170:171]
	global_load_dwordx4 v[126:129], v[114:115], off
	global_load_dwordx4 v[122:125], v[114:115], off offset:256
	v_lshl_add_u64 v[114:115], v[166:167], 0, v[172:173]
	global_load_dwordx4 v[118:121], v[114:115], off
	s_nop 0
	global_load_dwordx4 v[114:117], v[114:115], off offset:256
	s_waitcnt vmcnt(0)
	v_lshlrev_b32_e32 v198, 16, v186
	v_add_f32_e32 v198, v150, v198
	v_and_b32_e32 v150, 0xffff0000, v186
	v_add_f32_e32 v186, v151, v150
	v_lshlrev_b32_e32 v150, 16, v187
	v_add_f32_e32 v152, v152, v150
	v_and_b32_e32 v150, 0xffff0000, v187
	v_add_f32_e32 v153, v153, v150
	v_lshlrev_b32_e32 v150, 16, v188
	v_add_f32_e32 v187, v146, v150
	v_and_b32_e32 v146, 0xffff0000, v188
	v_add_f32_e32 v188, v147, v146
	v_lshlrev_b32_e32 v146, 16, v189
	v_add_f32_e32 v199, v148, v146
	v_and_b32_e32 v146, 0xffff0000, v189
	v_lshl_add_u64 v[150:151], s[18:19], 0, v[196:197]
	v_add_f32_e32 v189, v149, v146
	v_cvt_pk_bf16_f32 v146, v198, v186
	v_cvt_pk_bf16_f32 v147, v152, v153
	v_lshl_add_u64 v[150:151], v[150:151], 0, v[194:195]
	v_cvt_pk_bf16_f32 v148, v187, v188
	v_cvt_pk_bf16_f32 v149, v199, v189
	global_store_dwordx4 v[150:151], v[146:149], off
	s_nop 1
	v_mul_f32_e32 v146, v186, v186
	v_mul_f32_e32 v147, v153, v153
	v_fmac_f32_e32 v146, v198, v198
	v_fmac_f32_e32 v147, v152, v152
	v_add_f32_e32 v146, v146, v147
	v_mul_f32_e32 v147, v188, v188
	v_mul_f32_e32 v148, v189, v189
	v_fmac_f32_e32 v147, v187, v187
	v_fmac_f32_e32 v148, v199, v199
	v_add_f32_e32 v147, v147, v148
	v_add_f32_e32 v146, v146, v147
	v_lshlrev_b32_e32 v147, 16, v190
	v_add_f32_e32 v142, v142, v147
	v_and_b32_e32 v147, 0xffff0000, v190
	v_add_f32_e32 v143, v143, v147
	v_lshlrev_b32_e32 v147, 16, v191
	v_add_f32_e32 v144, v144, v147
	v_and_b32_e32 v147, 0xffff0000, v191
	v_add_f32_e32 v145, v145, v147
	v_lshlrev_b32_e32 v147, 16, v192
	v_add_f32_e32 v147, v138, v147
	v_and_b32_e32 v138, 0xffff0000, v192
	v_add_f32_e32 v148, v139, v138
	v_lshlrev_b32_e32 v138, 16, v193
	v_add_f32_e32 v149, v140, v138
	v_and_b32_e32 v138, 0xffff0000, v193
	v_add_f32_e32 v152, v141, v138
	v_cvt_pk_bf16_f32 v138, v142, v143
	v_cvt_pk_bf16_f32 v139, v144, v145
	v_cvt_pk_bf16_f32 v140, v147, v148
	v_cvt_pk_bf16_f32 v141, v149, v152
	global_store_dwordx4 v[150:151], v[138:141], off offset:256
	s_nop 1
	v_mul_f32_e32 v138, v143, v143
	v_mul_f32_e32 v139, v145, v145
	v_fmac_f32_e32 v138, v142, v142
	v_fmac_f32_e32 v139, v144, v144
	v_add_f32_e32 v138, v138, v139
	v_mul_f32_e32 v139, v148, v148
	v_mul_f32_e32 v140, v152, v152
	v_fmac_f32_e32 v139, v147, v147
	v_fmac_f32_e32 v140, v149, v149
	v_add_f32_e32 v139, v139, v140
	v_add_f32_e32 v138, v138, v139
	v_and_b32_e32 v140, 64, v243
	v_add_f32_e32 v139, v146, v138
	v_xor_b32_e32 v138, 16, v243
	v_add_u32_e32 v141, 64, v140
	v_cmp_lt_i32_e32 vcc, v138, v141
	s_nop 1
	v_cndmask_b32_e32 v138, v243, v138, vcc
	v_lshlrev_b32_e32 v138, 2, v138
	ds_bpermute_b32 v140, v138, v139
	s_waitcnt lgkmcnt(0)
	v_add_f32_e32 v140, v139, v140
	v_xor_b32_e32 v139, 32, v243
	v_cmp_lt_i32_e32 vcc, v139, v141
	s_nop 1
	v_cndmask_b32_e32 v139, v243, v139, vcc
	v_lshlrev_b32_e32 v139, 2, v139
	v_mov_b32_e32 v141, v140
	s_nop 1
	v_permlane32_swap_b32_e32 v141, v140
	s_and_saveexec_b64 s[18:19], s[4:5]
	s_cbranch_execz .LBB0_355
	s_waitcnt lgkmcnt(0)
	v_add_f32_e32 v140, v140, v141
	v_mul_f32_e32 v140, 0x49800000, v140
	v_trunc_f32_e32 v140, v140
	v_mul_f32_e32 v141, 0x2f800000, v140
	v_floor_f32_e32 v141, v141
	v_fmac_f32_e32 v140, 0xcf800000, v141
	v_cvt_u32_f32_e32 v140, v140
	v_cvt_u32_f32_e32 v141, v141
	v_lshl_add_u64 v[142:143], v[168:169], 3, s[34:35]
	global_atomic_add_x2 v[142:143], v[140:141], off
; __device__ __forceinline__ unsigned cvt_pk_bf16(float lo, float hi) { unsigned r; asm volatile("v_cvt_pk_bf16_f32 %0, %1, %2" : "=v"(r) : "v"(lo), "v"(hi)); return r; }
;     __device__ __forceinline__ void operator()(const f32x4 (&acc)[2][2][4][2], const Unit& u, int wr, int wc, int fr, int fq) const {
;     ...
;             for (int m = 0; m < 4; ++m) { const int row = row0 + ai * HALF + m * 16; const size_t off = (size_t)row * 1024 + col0; float s = 0.f;
; #pragma unroll
;                 for (int bj = 0; bj < 2; ++bj) { const u32x4 rw = raw[m][bj];
;                     f32x4 o0, o1;
;                     o0[0] = __uint_as_float(rw.x << 16) + acc[ai][bj][m][0][0]; o0[1] = __uint_as_float(rw.x & 0xffff0000u) + acc[ai][bj][m][0][1];
;                     o0[2] = __uint_as_float(rw.y << 16) + acc[ai][bj][m][0][2]; o0[3] = __uint_as_float(rw.y & 0xffff0000u) + acc[ai][bj][m][0][3];
;                     o1[0] = __uint_as_float(rw.z << 16) + acc[ai][bj][m][1][0]; o1[1] = __uint_as_float(rw.z & 0xffff0000u) + acc[ai][bj][m][1][1];
;                     o1[2] = __uint_as_float(rw.w << 16) + acc[ai][bj][m][1][2]; o1[3] = __uint_as_float(rw.w & 0xffff0000u) + acc[ai][bj][m][1][3];
;                     if (out) { *(f32x4*)(out + off + bj * HALF) = o0; *(f32x4*)(out + off + bj * HALF + 4) = o1; }
;                     else { u32x4 w; w.x = cvt_pk_bf16(o0[0], o0[1]); w.y = cvt_pk_bf16(o0[2], o0[3]); w.z = cvt_pk_bf16(o1[0], o1[1]); w.w = cvt_pk_bf16(o1[2], o1[3]); *(u32x4*)(xb + off + bj * HALF) = w;
;                         s += ((o0[0] * o0[0] + o0[1] * o0[1]) + (o0[2] * o0[2] + o0[3] * o0[3])) + ((o1[0] * o1[0] + o1[1] * o1[1]) + (o1[2] * o1[2] + o1[3] * o1[3])); } }
;                 if (!out) { s += __shfl_xor(s, 16); s += __shfl_xor(s, 32); if (fq == 0) atomicAdd(ssq_next + row, (unsigned long long)(s * 1048576.0f)); } }
.LBB0_355:
	s_or_b64 exec, exec, s[18:19]
	v_lshlrev_b32_e32 v140, 16, v134
	v_and_b32_e32 v134, 0xffff0000, v134
	v_add_f32_e32 v111, v111, v134
	v_lshlrev_b32_e32 v134, 16, v135
	v_add_f32_e32 v112, v112, v134
	v_and_b32_e32 v134, 0xffff0000, v135
	v_add_f32_e32 v113, v113, v134
	v_lshlrev_b32_e32 v134, 16, v136
	v_add_f32_e32 v134, v106, v134
	v_and_b32_e32 v106, 0xffff0000, v136
	v_add_f32_e32 v135, v107, v106
	v_lshlrev_b32_e32 v106, 16, v137
	v_add_f32_e32 v136, v108, v106
	v_and_b32_e32 v106, 0xffff0000, v137
	v_add_f32_e32 v110, v110, v140
	v_add_f32_e32 v137, v109, v106
	v_cvt_pk_bf16_f32 v106, v110, v111
	v_mul_f32_e32 v111, v111, v111
	v_fmac_f32_e32 v111, v110, v110
	v_mul_f32_e32 v110, v113, v113
	v_fmac_f32_e32 v110, v112, v112
	v_cvt_pk_bf16_f32 v107, v112, v113
	v_add_f32_e32 v110, v111, v110
	v_mul_f32_e32 v111, v135, v135
	v_mul_f32_e32 v112, v137, v137
	v_fmac_f32_e32 v111, v134, v134
	v_fmac_f32_e32 v112, v136, v136
	v_add_f32_e32 v111, v111, v112
	v_add_f32_e32 v110, v110, v111
	v_lshlrev_b32_e32 v111, 16, v130
	v_add_f32_e32 v102, v102, v111
	v_and_b32_e32 v111, 0xffff0000, v130
	v_add_f32_e32 v103, v103, v111
	v_lshlrev_b32_e32 v111, 16, v131
	v_add_f32_e32 v111, v104, v111
	v_and_b32_e32 v104, 0xffff0000, v131
	v_add_f32_e32 v112, v105, v104
	v_lshlrev_b32_e32 v104, 16, v132
	v_add_f32_e32 v113, v98, v104
	v_and_b32_e32 v98, 0xffff0000, v132
	v_add_f32_e32 v130, v99, v98
	v_lshlrev_b32_e32 v98, 16, v133
	v_add_f32_e32 v131, v100, v98
	v_and_b32_e32 v98, 0xffff0000, v133
	v_add_f32_e32 v132, v101, v98
	v_mul_f32_e32 v98, v103, v103
	v_mul_f32_e32 v99, v112, v112
	v_fmac_f32_e32 v98, v102, v102
	v_fmac_f32_e32 v99, v111, v111
	v_add_f32_e32 v98, v98, v99
	v_mul_f32_e32 v99, v130, v130
	v_mul_f32_e32 v100, v132, v132
	v_fmac_f32_e32 v99, v113, v113
	v_fmac_f32_e32 v100, v131, v131
	v_add_f32_e32 v99, v99, v100
	v_add_f32_e32 v98, v98, v99
	v_add_f32_e32 v101, v110, v98
	ds_bpermute_b32 v110, v138, v101
	v_readlane_b32 s18, v254, 15
	v_readlane_b32 s19, v254, 16
	v_cvt_pk_bf16_f32 v108, v134, v135
	v_cvt_pk_bf16_f32 v109, v136, v137
	s_nop 1
	v_lshl_add_u64 v[98:99], s[18:19], 0, v[180:181]
	v_lshl_add_u64 v[104:105], v[164:165], 1, v[98:99]
	s_waitcnt lgkmcnt(0)
	v_add_f32_e32 v98, v101, v110
	v_mov_b32_e32 v99, v98
	s_nop 1
	v_permlane32_swap_b32_e32 v99, v98
	global_store_dwordx4 v[104:105], v[106:109], off
	v_cvt_pk_bf16_f32 v100, v102, v103
	v_cvt_pk_bf16_f32 v101, v111, v112
	v_cvt_pk_bf16_f32 v102, v113, v130
	v_cvt_pk_bf16_f32 v103, v131, v132
	global_store_dwordx4 v[104:105], v[100:103], off offset:256
	s_and_saveexec_b64 s[18:19], s[4:5]
	s_cbranch_execz .LBB0_357
	s_waitcnt lgkmcnt(0)
	v_add_f32_e32 v98, v98, v99
	v_mul_f32_e32 v98, 0x49800000, v98
	v_trunc_f32_e32 v98, v98
	v_mul_f32_e32 v99, 0x2f800000, v98
	v_floor_f32_e32 v99, v99
	v_fmac_f32_e32 v98, 0xcf800000, v99
	v_cvt_u32_f32_e32 v98, v98
	v_cvt_u32_f32_e32 v99, v99
	v_lshl_add_u64 v[100:101], v[178:179], 3, s[34:35]
	global_atomic_add_x2 v[100:101], v[98:99], off
.LBB0_357:
	s_or_b64 exec, exec, s[18:19]
	v_lshlrev_b32_e32 v98, 16, v126
	v_add_f32_e32 v94, v94, v98
	v_and_b32_e32 v98, 0xffff0000, v126
	v_add_f32_e32 v95, v95, v98
	v_lshlrev_b32_e32 v98, 16, v127
	v_add_f32_e32 v96, v96, v98
	v_and_b32_e32 v98, 0xffff0000, v127
	v_add_f32_e32 v97, v97, v98
	v_lshlrev_b32_e32 v98, 16, v128
	v_add_f32_e32 v98, v90, v98
	v_and_b32_e32 v90, 0xffff0000, v128
	s_waitcnt lgkmcnt(0)
	v_add_f32_e32 v99, v91, v90
	v_lshlrev_b32_e32 v90, 16, v129
	v_add_f32_e32 v100, v92, v90
	v_and_b32_e32 v90, 0xffff0000, v129
	v_add_f32_e32 v101, v93, v90
	v_cvt_pk_bf16_f32 v90, v94, v95
	v_mul_f32_e32 v95, v95, v95
	v_fmac_f32_e32 v95, v94, v94
	v_mul_f32_e32 v94, v97, v97
	v_fmac_f32_e32 v94, v96, v96
	v_cvt_pk_bf16_f32 v91, v96, v97
	v_add_f32_e32 v94, v95, v94
	v_mul_f32_e32 v95, v99, v99
	v_mul_f32_e32 v96, v101, v101
	v_fmac_f32_e32 v95, v98, v98
	v_fmac_f32_e32 v96, v100, v100
	v_add_f32_e32 v95, v95, v96
	v_add_f32_e32 v94, v94, v95
	v_lshlrev_b32_e32 v95, 16, v122
	v_add_f32_e32 v86, v86, v95
	v_and_b32_e32 v95, 0xffff0000, v122
	v_add_f32_e32 v87, v87, v95
	v_lshlrev_b32_e32 v95, 16, v123
	v_add_f32_e32 v95, v88, v95
	v_and_b32_e32 v88, 0xffff0000, v123
	v_add_f32_e32 v96, v89, v88
	v_lshlrev_b32_e32 v88, 16, v124
	v_add_f32_e32 v97, v82, v88
	v_and_b32_e32 v82, 0xffff0000, v124
	v_cvt_pk_bf16_f32 v92, v98, v99
	v_add_f32_e32 v98, v83, v82
	v_lshlrev_b32_e32 v82, 16, v125
	v_add_f32_e32 v99, v84, v82
	v_and_b32_e32 v82, 0xffff0000, v125
	v_cvt_pk_bf16_f32 v93, v100, v101
	v_add_f32_e32 v100, v85, v82
	v_mul_f32_e32 v82, v87, v87
	v_mul_f32_e32 v83, v96, v96
	v_fmac_f32_e32 v82, v86, v86
	v_fmac_f32_e32 v83, v95, v95
	v_add_f32_e32 v82, v82, v83
	v_mul_f32_e32 v83, v98, v98
	v_mul_f32_e32 v84, v100, v100
	v_fmac_f32_e32 v83, v97, v97
	v_fmac_f32_e32 v84, v99, v99
	v_add_f32_e32 v83, v83, v84
	v_add_f32_e32 v82, v82, v83
	v_add_f32_e32 v85, v94, v82
	ds_bpermute_b32 v94, v138, v85
	v_readlane_b32 s18, v254, 15
	v_readlane_b32 s19, v254, 16
	s_nop 1
	v_lshl_add_u64 v[82:83], s[18:19], 0, v[176:177]
	v_lshl_add_u64 v[88:89], v[164:165], 1, v[82:83]
	s_waitcnt lgkmcnt(0)
	v_add_f32_e32 v82, v85, v94
	v_mov_b32_e32 v83, v82
	s_nop 1
	v_permlane32_swap_b32_e32 v83, v82
	global_store_dwordx4 v[88:89], v[90:93], off
	v_cvt_pk_bf16_f32 v84, v86, v87
	v_cvt_pk_bf16_f32 v85, v95, v96
	v_cvt_pk_bf16_f32 v86, v97, v98
	v_cvt_pk_bf16_f32 v87, v99, v100
	global_store_dwordx4 v[88:89], v[84:87], off offset:256
	s_and_saveexec_b64 s[18:19], s[4:5]
	s_cbranch_execz .LBB0_359
	s_waitcnt lgkmcnt(0)
	v_add_f32_e32 v82, v82, v83
	v_mul_f32_e32 v82, 0x49800000, v82
	v_trunc_f32_e32 v82, v82
	v_mul_f32_e32 v83, 0x2f800000, v82
	v_floor_f32_e32 v83, v83
	v_fmac_f32_e32 v82, 0xcf800000, v83
	v_cvt_u32_f32_e32 v82, v82
	v_cvt_u32_f32_e32 v83, v83
	v_lshl_add_u64 v[84:85], v[174:175], 3, s[34:35]
	global_atomic_add_x2 v[84:85], v[82:83], off
; __device__ __forceinline__ unsigned cvt_pk_bf16(float lo, float hi) { unsigned r; asm volatile("v_cvt_pk_bf16_f32 %0, %1, %2" : "=v"(r) : "v"(lo), "v"(hi)); return r; }
;     __device__ __forceinline__ void operator()(const f32x4 (&acc)[2][2][4][2], const Unit& u, int wr, int wc, int fr, int fq) const {
;     ...
;         for (int ai = 0; ai < 2; ++ai) {
;             u32x4 raw[4][2];
; #pragma unroll
;             for (int m = 0; m < 4; ++m)
; #pragma unroll
;                 for (int bj = 0; bj < 2; ++bj) raw[m][bj] = *(const u32x4*)(xb + (size_t)(row0 + ai * HALF + m * 16) * 1024 + col0 + bj * HALF);
; #pragma unroll
;             for (int m = 0; m < 4; ++m) { const int row = row0 + ai * HALF + m * 16; const size_t off = (size_t)row * 1024 + col0; float s = 0.f;
; #pragma unroll
;                 for (int bj = 0; bj < 2; ++bj) { const u32x4 rw = raw[m][bj];
;                     f32x4 o0, o1;
;                     o0[0] = __uint_as_float(rw.x << 16) + acc[ai][bj][m][0][0]; o0[1] = __uint_as_float(rw.x & 0xffff0000u) + acc[ai][bj][m][0][1];
;                     o0[2] = __uint_as_float(rw.y << 16) + acc[ai][bj][m][0][2]; o0[3] = __uint_as_float(rw.y & 0xffff0000u) + acc[ai][bj][m][0][3];
;                     o1[0] = __uint_as_float(rw.z << 16) + acc[ai][bj][m][1][0]; o1[1] = __uint_as_float(rw.z & 0xffff0000u) + acc[ai][bj][m][1][1];
;                     o1[2] = __uint_as_float(rw.w << 16) + acc[ai][bj][m][1][2]; o1[3] = __uint_as_float(rw.w & 0xffff0000u) + acc[ai][bj][m][1][3];
;                     if (out) { *(f32x4*)(out + off + bj * HALF) = o0; *(f32x4*)(out + off + bj * HALF + 4) = o1; }
;                     else { u32x4 w; w.x = cvt_pk_bf16(o0[0], o0[1]); w.y = cvt_pk_bf16(o0[2], o0[3]); w.z = cvt_pk_bf16(o1[0], o1[1]); w.w = cvt_pk_bf16(o1[2], o1[3]); *(u32x4*)(xb + off + bj * HALF) = w;
;                         s += ((o0[0] * o0[0] + o0[1] * o0[1]) + (o0[2] * o0[2] + o0[3] * o0[3])) + ((o1[0] * o1[0] + o1[1] * o1[1]) + (o1[2] * o1[2] + o1[3] * o1[3])); } }
;                 if (!out) { s += __shfl_xor(s, 16); s += __shfl_xor(s, 32); if (fq == 0) atomicAdd(ssq_next + row, (unsigned long long)(s * 1048576.0f)); } }
.LBB0_359:
	s_or_b64 exec, exec, s[18:19]
	v_lshlrev_b32_e32 v82, 16, v118
	v_add_f32_e32 v78, v78, v82
	v_and_b32_e32 v82, 0xffff0000, v118
	v_add_f32_e32 v79, v79, v82
	v_lshlrev_b32_e32 v82, 16, v119
	v_add_f32_e32 v80, v80, v82
	v_and_b32_e32 v82, 0xffff0000, v119
	v_add_f32_e32 v81, v81, v82
	v_lshlrev_b32_e32 v82, 16, v120
	v_add_f32_e32 v82, v74, v82
	v_and_b32_e32 v74, 0xffff0000, v120
	s_waitcnt lgkmcnt(0)
	v_add_f32_e32 v83, v75, v74
	v_lshlrev_b32_e32 v74, 16, v121
	v_add_f32_e32 v84, v76, v74
	v_and_b32_e32 v74, 0xffff0000, v121
	v_add_f32_e32 v85, v77, v74
	v_cvt_pk_bf16_f32 v74, v78, v79
	v_mul_f32_e32 v79, v79, v79
	v_fmac_f32_e32 v79, v78, v78
	v_mul_f32_e32 v78, v81, v81
	v_fmac_f32_e32 v78, v80, v80
	v_cvt_pk_bf16_f32 v75, v80, v81
	v_add_f32_e32 v78, v79, v78
	v_mul_f32_e32 v79, v83, v83
	v_mul_f32_e32 v80, v85, v85
	v_fmac_f32_e32 v79, v82, v82
	v_fmac_f32_e32 v80, v84, v84
	v_add_f32_e32 v79, v79, v80
	v_add_f32_e32 v78, v78, v79
	v_lshlrev_b32_e32 v79, 16, v114
	v_add_f32_e32 v70, v70, v79
	v_and_b32_e32 v79, 0xffff0000, v114
	v_add_f32_e32 v71, v71, v79
	v_lshlrev_b32_e32 v79, 16, v115
	v_add_f32_e32 v79, v72, v79
	v_and_b32_e32 v72, 0xffff0000, v115
	v_add_f32_e32 v80, v73, v72
	v_lshlrev_b32_e32 v72, 16, v116
	v_add_f32_e32 v81, v66, v72
	v_and_b32_e32 v66, 0xffff0000, v116
	v_cvt_pk_bf16_f32 v76, v82, v83
	v_add_f32_e32 v82, v67, v66
	v_lshlrev_b32_e32 v66, 16, v117
	v_add_f32_e32 v83, v68, v66
	v_and_b32_e32 v66, 0xffff0000, v117
	v_cvt_pk_bf16_f32 v77, v84, v85
	v_add_f32_e32 v84, v69, v66
	v_mul_f32_e32 v66, v71, v71
	v_mul_f32_e32 v67, v80, v80
	v_fmac_f32_e32 v66, v70, v70
	v_fmac_f32_e32 v67, v79, v79
	v_add_f32_e32 v66, v66, v67
	v_mul_f32_e32 v67, v82, v82
	v_mul_f32_e32 v68, v84, v84
	v_fmac_f32_e32 v67, v81, v81
	v_fmac_f32_e32 v68, v83, v83
	v_add_f32_e32 v67, v67, v68
	v_add_f32_e32 v66, v66, v67
	v_add_f32_e32 v69, v78, v66
	ds_bpermute_b32 v78, v138, v69
	v_readlane_b32 s18, v254, 15
	v_readlane_b32 s19, v254, 16
	s_nop 1
	v_lshl_add_u64 v[66:67], s[18:19], 0, v[172:173]
	v_lshl_add_u64 v[72:73], v[164:165], 1, v[66:67]
	s_waitcnt lgkmcnt(0)
	v_add_f32_e32 v66, v69, v78
	v_mov_b32_e32 v67, v66
	s_nop 1
	v_permlane32_swap_b32_e32 v67, v66
	global_store_dwordx4 v[72:73], v[74:77], off
	v_cvt_pk_bf16_f32 v68, v70, v71
	v_cvt_pk_bf16_f32 v69, v79, v80
	v_cvt_pk_bf16_f32 v70, v81, v82
	v_cvt_pk_bf16_f32 v71, v83, v84
	global_store_dwordx4 v[72:73], v[68:71], off offset:256
	s_and_saveexec_b64 s[18:19], s[4:5]
	s_cbranch_execz .LBB0_361
	s_waitcnt lgkmcnt(0)
	v_add_f32_e32 v66, v66, v67
	v_mul_f32_e32 v66, 0x49800000, v66
	v_trunc_f32_e32 v66, v66
	v_mul_f32_e32 v67, 0x2f800000, v66
	v_floor_f32_e32 v67, v67
	v_fmac_f32_e32 v66, 0xcf800000, v67
	v_cvt_u32_f32_e32 v66, v66
	v_cvt_u32_f32_e32 v67, v67
	v_lshl_add_u64 v[68:69], v[170:171], 3, s[34:35]
	global_atomic_add_x2 v[68:69], v[66:67], off
.LBB0_361:
	s_or_b64 exec, exec, s[18:19]
	v_add_u32_e32 v106, 0x80, v168
	v_ashrrev_i32_e32 v107, 31, v106
	v_lshlrev_b64 v[112:113], 11, v[106:107]
	s_waitcnt lgkmcnt(0)
	v_lshl_add_u64 v[66:67], v[166:167], 0, v[112:113]
	global_load_dwordx4 v[108:111], v[66:67], off
	global_load_dwordx4 v[90:93], v[66:67], off offset:256
	v_add_u32_e32 v102, 0x90, v168
	v_ashrrev_i32_e32 v103, 31, v102
	v_add_u32_e32 v98, 0xa0, v168
	v_lshlrev_b64 v[104:105], 11, v[102:103]
	v_ashrrev_i32_e32 v99, 31, v98
	v_add_u32_e32 v94, 0xb0, v168
	v_lshl_add_u64 v[66:67], v[166:167], 0, v[104:105]
	v_lshlrev_b64 v[100:101], 11, v[98:99]
	v_ashrrev_i32_e32 v95, 31, v94
	global_load_dwordx4 v[86:89], v[66:67], off
	global_load_dwordx4 v[82:85], v[66:67], off offset:256
	v_lshl_add_u64 v[66:67], v[166:167], 0, v[100:101]
	v_lshlrev_b64 v[96:97], 11, v[94:95]
	global_load_dwordx4 v[78:81], v[66:67], off
	global_load_dwordx4 v[74:77], v[66:67], off offset:256
	v_lshl_add_u64 v[66:67], v[166:167], 0, v[96:97]
	global_load_dwordx4 v[70:73], v[66:67], off
	s_nop 0
	global_load_dwordx4 v[66:69], v[66:67], off offset:256
	v_readlane_b32 s18, v254, 15
	v_readlane_b32 s19, v254, 16
	s_waitcnt vmcnt(7)
	v_lshlrev_b32_e32 v114, 16, v108
	v_add_f32_e32 v114, v62, v114
	v_and_b32_e32 v62, 0xffff0000, v108
	v_add_f32_e32 v108, v63, v62
	v_lshlrev_b32_e32 v62, 16, v109
	v_add_f32_e32 v64, v64, v62
	v_and_b32_e32 v62, 0xffff0000, v109
	v_add_f32_e32 v65, v65, v62
	v_lshlrev_b32_e32 v62, 16, v110
	v_add_f32_e32 v109, v58, v62
	v_and_b32_e32 v58, 0xffff0000, v110
	v_add_f32_e32 v110, v59, v58
	v_lshlrev_b32_e32 v58, 16, v111
	v_add_f32_e32 v115, v60, v58
	v_and_b32_e32 v58, 0xffff0000, v111
	v_lshl_add_u64 v[62:63], s[18:19], 0, v[112:113]
	v_add_f32_e32 v111, v61, v58
	v_cvt_pk_bf16_f32 v58, v114, v108
	v_cvt_pk_bf16_f32 v59, v64, v65
	v_lshl_add_u64 v[62:63], v[164:165], 1, v[62:63]
	v_cvt_pk_bf16_f32 v60, v109, v110
	v_cvt_pk_bf16_f32 v61, v115, v111
	global_store_dwordx4 v[62:63], v[58:61], off
	s_nop 1
	v_mul_f32_e32 v58, v108, v108
	v_mul_f32_e32 v59, v65, v65
	v_fmac_f32_e32 v58, v114, v114
	v_fmac_f32_e32 v59, v64, v64
	v_add_f32_e32 v58, v58, v59
	v_mul_f32_e32 v59, v110, v110
	v_mul_f32_e32 v60, v111, v111
	v_fmac_f32_e32 v59, v109, v109
	v_fmac_f32_e32 v60, v115, v115
	v_add_f32_e32 v59, v59, v60
	v_add_f32_e32 v58, v58, v59
	s_waitcnt vmcnt(7)
	v_lshlrev_b32_e32 v59, 16, v90
	v_add_f32_e32 v54, v54, v59
	v_and_b32_e32 v59, 0xffff0000, v90
	v_add_f32_e32 v55, v55, v59
	v_lshlrev_b32_e32 v59, 16, v91
	v_add_f32_e32 v56, v56, v59
	v_and_b32_e32 v59, 0xffff0000, v91
	v_add_f32_e32 v57, v57, v59
	v_lshlrev_b32_e32 v59, 16, v92
	v_add_f32_e32 v59, v50, v59
	v_and_b32_e32 v50, 0xffff0000, v92
	v_add_f32_e32 v60, v51, v50
	v_lshlrev_b32_e32 v50, 16, v93
	v_add_f32_e32 v61, v52, v50
	v_and_b32_e32 v50, 0xffff0000, v93
	v_add_f32_e32 v64, v53, v50
	v_cvt_pk_bf16_f32 v50, v54, v55
	v_cvt_pk_bf16_f32 v51, v56, v57
	v_cvt_pk_bf16_f32 v52, v59, v60
	v_cvt_pk_bf16_f32 v53, v61, v64
	global_store_dwordx4 v[62:63], v[50:53], off offset:256
	s_nop 1
	v_mul_f32_e32 v50, v55, v55
	v_mul_f32_e32 v51, v57, v57
	v_fmac_f32_e32 v50, v54, v54
	v_fmac_f32_e32 v51, v56, v56
	v_add_f32_e32 v50, v50, v51
	v_mul_f32_e32 v51, v60, v60
	v_mul_f32_e32 v52, v64, v64
	v_fmac_f32_e32 v51, v59, v59
	v_fmac_f32_e32 v52, v61, v61
	v_add_f32_e32 v51, v51, v52
	v_add_f32_e32 v50, v50, v51
	v_add_f32_e32 v50, v58, v50
	ds_bpermute_b32 v51, v138, v50
	s_waitcnt lgkmcnt(0)
	v_add_f32_e32 v50, v50, v51
	v_mov_b32_e32 v51, v50
	s_nop 1
	v_permlane32_swap_b32_e32 v51, v50
	s_and_saveexec_b64 s[18:19], s[4:5]
	s_cbranch_execz .LBB0_363
	s_waitcnt lgkmcnt(0)
	v_add_f32_e32 v50, v50, v51
	v_mul_f32_e32 v50, 0x49800000, v50
	v_trunc_f32_e32 v50, v50
	v_mul_f32_e32 v51, 0x2f800000, v50
	v_floor_f32_e32 v51, v51
	v_fmac_f32_e32 v50, 0xcf800000, v51
	v_cvt_u32_f32_e32 v50, v50
	v_cvt_u32_f32_e32 v51, v51
	v_lshl_add_u64 v[52:53], v[106:107], 3, s[34:35]
	global_atomic_add_x2 v[52:53], v[50:51], off
; __device__ __forceinline__ unsigned cvt_pk_bf16(float lo, float hi) { unsigned r; asm volatile("v_cvt_pk_bf16_f32 %0, %1, %2" : "=v"(r) : "v"(lo), "v"(hi)); return r; }
;     __device__ __forceinline__ void operator()(const f32x4 (&acc)[2][2][4][2], const Unit& u, int wr, int wc, int fr, int fq) const {
;     ...
;             for (int m = 0; m < 4; ++m) { const int row = row0 + ai * HALF + m * 16; const size_t off = (size_t)row * 1024 + col0; float s = 0.f;
; #pragma unroll
;                 for (int bj = 0; bj < 2; ++bj) { const u32x4 rw = raw[m][bj];
;                     f32x4 o0, o1;
;                     o0[0] = __uint_as_float(rw.x << 16) + acc[ai][bj][m][0][0]; o0[1] = __uint_as_float(rw.x & 0xffff0000u) + acc[ai][bj][m][0][1];
;                     o0[2] = __uint_as_float(rw.y << 16) + acc[ai][bj][m][0][2]; o0[3] = __uint_as_float(rw.y & 0xffff0000u) + acc[ai][bj][m][0][3];
;                     o1[0] = __uint_as_float(rw.z << 16) + acc[ai][bj][m][1][0]; o1[1] = __uint_as_float(rw.z & 0xffff0000u) + acc[ai][bj][m][1][1];
;                     o1[2] = __uint_as_float(rw.w << 16) + acc[ai][bj][m][1][2]; o1[3] = __uint_as_float(rw.w & 0xffff0000u) + acc[ai][bj][m][1][3];
;                     if (out) { *(f32x4*)(out + off + bj * HALF) = o0; *(f32x4*)(out + off + bj * HALF + 4) = o1; }
;                     else { u32x4 w; w.x = cvt_pk_bf16(o0[0], o0[1]); w.y = cvt_pk_bf16(o0[2], o0[3]); w.z = cvt_pk_bf16(o1[0], o1[1]); w.w = cvt_pk_bf16(o1[2], o1[3]); *(u32x4*)(xb + off + bj * HALF) = w;
;                         s += ((o0[0] * o0[0] + o0[1] * o0[1]) + (o0[2] * o0[2] + o0[3] * o0[3])) + ((o1[0] * o1[0] + o1[1] * o1[1]) + (o1[2] * o1[2] + o1[3] * o1[3])); } }
;                 if (!out) { s += __shfl_xor(s, 16); s += __shfl_xor(s, 32); if (fq == 0) atomicAdd(ssq_next + row, (unsigned long long)(s * 1048576.0f)); } }
.LBB0_363:
	s_or_b64 exec, exec, s[18:19]
	s_waitcnt vmcnt(7)
	v_lshlrev_b32_e32 v50, 16, v86
	v_add_f32_e32 v46, v46, v50
	v_and_b32_e32 v50, 0xffff0000, v86
	v_add_f32_e32 v47, v47, v50
	v_lshlrev_b32_e32 v50, 16, v87
	v_add_f32_e32 v48, v48, v50
	v_and_b32_e32 v50, 0xffff0000, v87
	v_add_f32_e32 v49, v49, v50
	v_lshlrev_b32_e32 v50, 16, v88
	v_add_f32_e32 v50, v42, v50
	v_and_b32_e32 v42, 0xffff0000, v88
	s_waitcnt lgkmcnt(0)
	v_add_f32_e32 v51, v43, v42
	v_lshlrev_b32_e32 v42, 16, v89
	v_add_f32_e32 v52, v44, v42
	v_and_b32_e32 v42, 0xffff0000, v89
	v_add_f32_e32 v53, v45, v42
	v_cvt_pk_bf16_f32 v42, v46, v47
	v_mul_f32_e32 v47, v47, v47
	v_fmac_f32_e32 v47, v46, v46
	v_mul_f32_e32 v46, v49, v49
	v_fmac_f32_e32 v46, v48, v48
	v_cvt_pk_bf16_f32 v43, v48, v49
	v_add_f32_e32 v46, v47, v46
	v_mul_f32_e32 v47, v51, v51
	v_mul_f32_e32 v48, v53, v53
	v_fmac_f32_e32 v47, v50, v50
	v_fmac_f32_e32 v48, v52, v52
	v_add_f32_e32 v47, v47, v48
	v_add_f32_e32 v46, v46, v47
	s_waitcnt vmcnt(6)
	v_lshlrev_b32_e32 v47, 16, v82
	v_add_f32_e32 v38, v38, v47
	v_and_b32_e32 v47, 0xffff0000, v82
	v_add_f32_e32 v39, v39, v47
	v_lshlrev_b32_e32 v47, 16, v83
	v_add_f32_e32 v47, v40, v47
	v_and_b32_e32 v40, 0xffff0000, v83
	v_add_f32_e32 v48, v41, v40
	v_lshlrev_b32_e32 v40, 16, v84
	v_add_f32_e32 v49, v34, v40
	v_and_b32_e32 v34, 0xffff0000, v84
	v_cvt_pk_bf16_f32 v44, v50, v51
	v_add_f32_e32 v50, v35, v34
	v_lshlrev_b32_e32 v34, 16, v85
	v_add_f32_e32 v51, v36, v34
	v_and_b32_e32 v34, 0xffff0000, v85
	v_cvt_pk_bf16_f32 v45, v52, v53
	v_add_f32_e32 v52, v37, v34
	v_mul_f32_e32 v34, v39, v39
	v_mul_f32_e32 v35, v48, v48
	v_fmac_f32_e32 v34, v38, v38
	v_fmac_f32_e32 v35, v47, v47
	v_add_f32_e32 v34, v34, v35
	v_mul_f32_e32 v35, v50, v50
	v_mul_f32_e32 v36, v52, v52
	v_fmac_f32_e32 v35, v49, v49
	v_fmac_f32_e32 v36, v51, v51
	v_add_f32_e32 v35, v35, v36
	v_add_f32_e32 v34, v34, v35
	v_add_f32_e32 v37, v46, v34
	ds_bpermute_b32 v46, v138, v37
	v_readlane_b32 s18, v254, 15
	v_readlane_b32 s19, v254, 16
	s_nop 1
	v_lshl_add_u64 v[34:35], s[18:19], 0, v[104:105]
	v_lshl_add_u64 v[40:41], v[164:165], 1, v[34:35]
	s_waitcnt lgkmcnt(0)
	v_add_f32_e32 v34, v37, v46
	v_mov_b32_e32 v35, v34
	s_nop 1
	v_permlane32_swap_b32_e32 v35, v34
	global_store_dwordx4 v[40:41], v[42:45], off
	v_cvt_pk_bf16_f32 v36, v38, v39
	v_cvt_pk_bf16_f32 v37, v47, v48
	v_cvt_pk_bf16_f32 v38, v49, v50
	v_cvt_pk_bf16_f32 v39, v51, v52
	global_store_dwordx4 v[40:41], v[36:39], off offset:256
	s_and_saveexec_b64 s[18:19], s[4:5]
	s_cbranch_execz .LBB0_365
	s_waitcnt lgkmcnt(0)
	v_add_f32_e32 v34, v34, v35
	v_mul_f32_e32 v34, 0x49800000, v34
	v_trunc_f32_e32 v34, v34
	v_mul_f32_e32 v35, 0x2f800000, v34
	v_floor_f32_e32 v35, v35
	v_fmac_f32_e32 v34, 0xcf800000, v35
	v_cvt_u32_f32_e32 v34, v34
	v_cvt_u32_f32_e32 v35, v35
	v_lshl_add_u64 v[36:37], v[102:103], 3, s[34:35]
	global_atomic_add_x2 v[36:37], v[34:35], off
; __device__ __forceinline__ unsigned cvt_pk_bf16(float lo, float hi) { unsigned r; asm volatile("v_cvt_pk_bf16_f32 %0, %1, %2" : "=v"(r) : "v"(lo), "v"(hi)); return r; }
;     __device__ __forceinline__ void operator()(const f32x4 (&acc)[2][2][4][2], const Unit& u, int wr, int wc, int fr, int fq) const {
;     ...
;             for (int m = 0; m < 4; ++m) { const int row = row0 + ai * HALF + m * 16; const size_t off = (size_t)row * 1024 + col0; float s = 0.f;
; #pragma unroll
;                 for (int bj = 0; bj < 2; ++bj) { const u32x4 rw = raw[m][bj];
;                     f32x4 o0, o1;
;                     o0[0] = __uint_as_float(rw.x << 16) + acc[ai][bj][m][0][0]; o0[1] = __uint_as_float(rw.x & 0xffff0000u) + acc[ai][bj][m][0][1];
;                     o0[2] = __uint_as_float(rw.y << 16) + acc[ai][bj][m][0][2]; o0[3] = __uint_as_float(rw.y & 0xffff0000u) + acc[ai][bj][m][0][3];
;                     o1[0] = __uint_as_float(rw.z << 16) + acc[ai][bj][m][1][0]; o1[1] = __uint_as_float(rw.z & 0xffff0000u) + acc[ai][bj][m][1][1];
;                     o1[2] = __uint_as_float(rw.w << 16) + acc[ai][bj][m][1][2]; o1[3] = __uint_as_float(rw.w & 0xffff0000u) + acc[ai][bj][m][1][3];
;                     if (out) { *(f32x4*)(out + off + bj * HALF) = o0; *(f32x4*)(out + off + bj * HALF + 4) = o1; }
;                     else { u32x4 w; w.x = cvt_pk_bf16(o0[0], o0[1]); w.y = cvt_pk_bf16(o0[2], o0[3]); w.z = cvt_pk_bf16(o1[0], o1[1]); w.w = cvt_pk_bf16(o1[2], o1[3]); *(u32x4*)(xb + off + bj * HALF) = w;
;                         s += ((o0[0] * o0[0] + o0[1] * o0[1]) + (o0[2] * o0[2] + o0[3] * o0[3])) + ((o1[0] * o1[0] + o1[1] * o1[1]) + (o1[2] * o1[2] + o1[3] * o1[3])); } }
;                 if (!out) { s += __shfl_xor(s, 16); s += __shfl_xor(s, 32); if (fq == 0) atomicAdd(ssq_next + row, (unsigned long long)(s * 1048576.0f)); } }
.LBB0_365:
	s_or_b64 exec, exec, s[18:19]
	s_waitcnt vmcnt(7)
	v_lshlrev_b32_e32 v34, 16, v78
	v_add_f32_e32 v30, v30, v34
	v_and_b32_e32 v34, 0xffff0000, v78
	v_add_f32_e32 v31, v31, v34
	v_lshlrev_b32_e32 v34, 16, v79
	v_add_f32_e32 v32, v32, v34
	v_and_b32_e32 v34, 0xffff0000, v79
	v_add_f32_e32 v33, v33, v34
	v_lshlrev_b32_e32 v34, 16, v80
	v_add_f32_e32 v34, v26, v34
	v_and_b32_e32 v26, 0xffff0000, v80
	s_waitcnt lgkmcnt(0)
	v_add_f32_e32 v35, v27, v26
	v_lshlrev_b32_e32 v26, 16, v81
	v_add_f32_e32 v36, v28, v26
	v_and_b32_e32 v26, 0xffff0000, v81
	v_add_f32_e32 v37, v29, v26
	v_cvt_pk_bf16_f32 v26, v30, v31
	v_mul_f32_e32 v31, v31, v31
	v_fmac_f32_e32 v31, v30, v30
	v_mul_f32_e32 v30, v33, v33
	v_fmac_f32_e32 v30, v32, v32
	v_cvt_pk_bf16_f32 v27, v32, v33
	v_add_f32_e32 v30, v31, v30
	v_mul_f32_e32 v31, v35, v35
	v_mul_f32_e32 v32, v37, v37
	v_fmac_f32_e32 v31, v34, v34
	v_fmac_f32_e32 v32, v36, v36
	v_add_f32_e32 v31, v31, v32
	v_add_f32_e32 v30, v30, v31
	s_waitcnt vmcnt(6)
	v_lshlrev_b32_e32 v31, 16, v74
	v_add_f32_e32 v22, v22, v31
	v_and_b32_e32 v31, 0xffff0000, v74
	v_add_f32_e32 v23, v23, v31
	v_lshlrev_b32_e32 v31, 16, v75
	v_add_f32_e32 v31, v24, v31
	v_and_b32_e32 v24, 0xffff0000, v75
	v_add_f32_e32 v32, v25, v24
	v_lshlrev_b32_e32 v24, 16, v76
	v_add_f32_e32 v33, v18, v24
	v_and_b32_e32 v18, 0xffff0000, v76
	v_cvt_pk_bf16_f32 v28, v34, v35
	v_add_f32_e32 v34, v19, v18
	v_lshlrev_b32_e32 v18, 16, v77
	v_add_f32_e32 v35, v20, v18
	v_and_b32_e32 v18, 0xffff0000, v77
	v_cvt_pk_bf16_f32 v29, v36, v37
	v_add_f32_e32 v36, v21, v18
	v_mul_f32_e32 v18, v23, v23
	v_mul_f32_e32 v19, v32, v32
	v_fmac_f32_e32 v18, v22, v22
	v_fmac_f32_e32 v19, v31, v31
	v_add_f32_e32 v18, v18, v19
	v_mul_f32_e32 v19, v34, v34
	v_mul_f32_e32 v20, v36, v36
	v_fmac_f32_e32 v19, v33, v33
	v_fmac_f32_e32 v20, v35, v35
	v_add_f32_e32 v19, v19, v20
	v_add_f32_e32 v18, v18, v19
	v_add_f32_e32 v21, v30, v18
	ds_bpermute_b32 v30, v138, v21
	v_readlane_b32 s18, v254, 15
	v_readlane_b32 s19, v254, 16
	s_nop 1
	v_lshl_add_u64 v[18:19], s[18:19], 0, v[100:101]
	v_lshl_add_u64 v[24:25], v[164:165], 1, v[18:19]
	s_waitcnt lgkmcnt(0)
	v_add_f32_e32 v18, v21, v30
	v_mov_b32_e32 v19, v18
	s_nop 1
	v_permlane32_swap_b32_e32 v19, v18
	global_store_dwordx4 v[24:25], v[26:29], off
	v_cvt_pk_bf16_f32 v20, v22, v23
	v_cvt_pk_bf16_f32 v21, v31, v32
	v_cvt_pk_bf16_f32 v22, v33, v34
	v_cvt_pk_bf16_f32 v23, v35, v36
	global_store_dwordx4 v[24:25], v[20:23], off offset:256
	s_and_saveexec_b64 s[18:19], s[4:5]
	s_cbranch_execz .LBB0_367
	s_waitcnt lgkmcnt(0)
	v_add_f32_e32 v18, v18, v19
	v_mul_f32_e32 v18, 0x49800000, v18
	v_trunc_f32_e32 v18, v18
	v_mul_f32_e32 v19, 0x2f800000, v18
	v_floor_f32_e32 v19, v19
	v_fmac_f32_e32 v18, 0xcf800000, v19
	v_cvt_u32_f32_e32 v18, v18
	v_cvt_u32_f32_e32 v19, v19
	v_lshl_add_u64 v[20:21], v[98:99], 3, s[34:35]
	global_atomic_add_x2 v[20:21], v[18:19], off
.LBB0_367:
	s_or_b64 exec, exec, s[18:19]
	s_waitcnt vmcnt(7)
	v_lshlrev_b32_e32 v18, 16, v70
	v_add_f32_e32 v14, v14, v18
	v_and_b32_e32 v18, 0xffff0000, v70
	v_add_f32_e32 v15, v15, v18
	v_lshlrev_b32_e32 v18, 16, v71
	v_add_f32_e32 v16, v16, v18
	v_and_b32_e32 v18, 0xffff0000, v71
	v_add_f32_e32 v17, v17, v18
	v_lshlrev_b32_e32 v18, 16, v72
	v_add_f32_e32 v18, v10, v18
	v_and_b32_e32 v10, 0xffff0000, v72
	s_waitcnt lgkmcnt(0)
	v_add_f32_e32 v19, v11, v10
	v_lshlrev_b32_e32 v10, 16, v73
	v_add_f32_e32 v20, v12, v10
	v_and_b32_e32 v10, 0xffff0000, v73
	v_add_f32_e32 v21, v13, v10
	v_cvt_pk_bf16_f32 v10, v14, v15
	v_mul_f32_e32 v15, v15, v15
	v_fmac_f32_e32 v15, v14, v14
	v_mul_f32_e32 v14, v17, v17
	v_fmac_f32_e32 v14, v16, v16
	v_cvt_pk_bf16_f32 v11, v16, v17
	v_add_f32_e32 v14, v15, v14
	v_mul_f32_e32 v15, v19, v19
	v_mul_f32_e32 v16, v21, v21
	v_fmac_f32_e32 v15, v18, v18
	v_fmac_f32_e32 v16, v20, v20
	v_add_f32_e32 v15, v15, v16
	v_add_f32_e32 v14, v14, v15
	s_waitcnt vmcnt(6)
	v_lshlrev_b32_e32 v15, 16, v66
	v_add_f32_e32 v6, v6, v15
	v_and_b32_e32 v15, 0xffff0000, v66
	v_add_f32_e32 v7, v7, v15
	v_lshlrev_b32_e32 v15, 16, v67
	v_add_f32_e32 v15, v8, v15
	v_and_b32_e32 v8, 0xffff0000, v67
	v_add_f32_e32 v16, v9, v8
	v_lshlrev_b32_e32 v8, 16, v68
	v_add_f32_e32 v17, v2, v8
	v_and_b32_e32 v2, 0xffff0000, v68
	v_cvt_pk_bf16_f32 v12, v18, v19
	v_add_f32_e32 v18, v3, v2
	v_lshlrev_b32_e32 v2, 16, v69
	v_add_f32_e32 v19, v4, v2
	v_and_b32_e32 v2, 0xffff0000, v69
	v_cvt_pk_bf16_f32 v13, v20, v21
	v_add_f32_e32 v20, v5, v2
	v_mul_f32_e32 v2, v7, v7
	v_mul_f32_e32 v3, v16, v16
	v_fmac_f32_e32 v2, v6, v6
	v_fmac_f32_e32 v3, v15, v15
	v_add_f32_e32 v2, v2, v3
	v_mul_f32_e32 v3, v18, v18
	v_mul_f32_e32 v4, v20, v20
	v_fmac_f32_e32 v3, v17, v17
	v_fmac_f32_e32 v4, v19, v19
	v_add_f32_e32 v3, v3, v4
	v_add_f32_e32 v2, v2, v3
	v_add_f32_e32 v5, v14, v2
	ds_bpermute_b32 v14, v138, v5
	v_readlane_b32 s18, v254, 15
	v_readlane_b32 s19, v254, 16
	s_nop 1
	v_lshl_add_u64 v[2:3], s[18:19], 0, v[96:97]
	v_lshl_add_u64 v[8:9], v[164:165], 1, v[2:3]
	s_waitcnt lgkmcnt(0)
	v_add_f32_e32 v2, v5, v14
	v_mov_b32_e32 v3, v2
	s_nop 1
	v_permlane32_swap_b32_e32 v3, v2
	global_store_dwordx4 v[8:9], v[10:13], off
	v_cvt_pk_bf16_f32 v4, v6, v7
	v_cvt_pk_bf16_f32 v5, v15, v16
	v_cvt_pk_bf16_f32 v6, v17, v18
	v_cvt_pk_bf16_f32 v7, v19, v20
	global_store_dwordx4 v[8:9], v[4:7], off offset:256
	s_and_saveexec_b64 s[18:19], s[4:5]
	s_cbranch_execz .LBB0_369
	s_waitcnt lgkmcnt(0)
	v_add_f32_e32 v2, v2, v3
	v_mul_f32_e32 v2, 0x49800000, v2
	v_trunc_f32_e32 v2, v2
	v_mul_f32_e32 v3, 0x2f800000, v2
	v_floor_f32_e32 v3, v3
	v_fmac_f32_e32 v2, 0xcf800000, v3
	v_cvt_u32_f32_e32 v2, v2
	v_cvt_u32_f32_e32 v3, v3
	v_lshl_add_u64 v[4:5], v[94:95], 3, s[34:35]
	global_atomic_add_x2 v[4:5], v[2:3], off

;     __device__ __forceinline__ void operator()(const f32x4 (&acc)[2][2][4][2], const Unit& u, int wr, int wc, int fr, int fq) const {
;     ...
;                 if (!out) { s += __shfl_xor(s, 16); s += __shfl_xor(s, 32); if (fq == 0) atomicAdd(ssq_next + row, (unsigned long long)(s * 1048576.0f)); } }
.LBB0_515:
	v_cndmask_b32_e64 v114, 0, 1, s[20:21]
	v_readlane_b32 s26, v254, 37
	v_cmp_ne_u32_e64 s[10:11], 1, v114
	s_andn2_b64 vcc, exec, s[20:21]
	v_readlane_b32 s27, v254, 38
	s_cbranch_vccnz .LBB0_519
	v_and_b32_e32 v115, 64, v243
	v_xor_b32_e32 v114, 16, v243
	v_add_u32_e32 v115, 64, v115
	v_cmp_lt_i32_e32 vcc, v114, v115
	v_xor_b32_e32 v116, 32, v243
	s_nop 0
	v_cndmask_b32_e32 v114, v243, v114, vcc
	v_lshlrev_b32_e32 v114, 2, v114
	ds_bpermute_b32 v114, v114, v190
	v_cmp_lt_i32_e32 vcc, v116, v115
	s_waitcnt lgkmcnt(0)
	v_add_f32_e32 v114, v190, v114
	v_cndmask_b32_e32 v115, v243, v116, vcc
	v_lshlrev_b32_e32 v115, 2, v115
	v_mov_b32_e32 v115, v114
	s_nop 1
	v_permlane32_swap_b32_e32 v115, v114
	s_and_saveexec_b64 s[26:27], s[4:5]
	s_cbranch_execz .LBB0_518
	s_waitcnt lgkmcnt(0)
	v_add_f32_e32 v114, v114, v115
	v_mul_f32_e32 v114, 0x49800000, v114
	v_trunc_f32_e32 v114, v114
	v_mul_f32_e32 v115, 0x2f800000, v114
	v_floor_f32_e32 v115, v115
	v_fmac_f32_e32 v114, 0xcf800000, v115
	v_cvt_u32_f32_e32 v114, v114
	v_cvt_u32_f32_e32 v115, v115
	v_lshl_add_u64 v[116:117], v[168:169], 3, s[16:17]
	global_atomic_add_x2 v[116:117], v[114:115], off

;     __device__ __forceinline__ void operator()(const f32x4 (&acc)[2][2][4][2], const Unit& u, int wr, int wc, int fr, int fq) const {
;     ...
;                 if (!out) { s += __shfl_xor(s, 16); s += __shfl_xor(s, 32); if (fq == 0) atomicAdd(ssq_next + row, (unsigned long long)(s * 1048576.0f)); } }
.LBB0_526:
	v_readlane_b32 s26, v254, 37
	s_and_b64 vcc, exec, s[10:11]
	v_readlane_b32 s27, v254, 38
	s_cbranch_vccnz .LBB0_530
	v_and_b32_e32 v99, 64, v243
	v_xor_b32_e32 v98, 16, v243
	v_add_u32_e32 v99, 64, v99
	v_cmp_lt_i32_e32 vcc, v98, v99
	v_xor_b32_e32 v100, 32, v243
	s_nop 0
	v_cndmask_b32_e32 v98, v243, v98, vcc
	v_lshlrev_b32_e32 v98, 2, v98
	ds_bpermute_b32 v98, v98, v112
	v_cmp_lt_i32_e32 vcc, v100, v99
	s_waitcnt lgkmcnt(0)
	v_add_f32_e32 v98, v112, v98
	v_cndmask_b32_e32 v99, v243, v100, vcc
	v_lshlrev_b32_e32 v99, 2, v99
	v_mov_b32_e32 v99, v98
	s_nop 1
	v_permlane32_swap_b32_e32 v99, v98
	s_and_saveexec_b64 s[26:27], s[4:5]
	s_cbranch_execz .LBB0_529
	s_waitcnt lgkmcnt(0)
	v_add_f32_e32 v98, v98, v99
	v_mul_f32_e32 v98, 0x49800000, v98
	v_trunc_f32_e32 v98, v98
	v_mul_f32_e32 v99, 0x2f800000, v98
	v_floor_f32_e32 v99, v99
	v_fmac_f32_e32 v98, 0xcf800000, v99
	v_cvt_u32_f32_e32 v98, v98
	v_cvt_u32_f32_e32 v99, v99
	v_lshl_add_u64 v[100:101], v[168:169], 3, s[16:17]
	global_atomic_add_x2 v[100:101], v[98:99], off offset:128

;     __device__ __forceinline__ void operator()(const f32x4 (&acc)[2][2][4][2], const Unit& u, int wr, int wc, int fr, int fq) const {
;     ...
;                 if (!out) { s += __shfl_xor(s, 16); s += __shfl_xor(s, 32); if (fq == 0) atomicAdd(ssq_next + row, (unsigned long long)(s * 1048576.0f)); } }
.LBB0_537:
	v_readlane_b32 s26, v254, 37
	s_and_b64 vcc, exec, s[10:11]
	v_readlane_b32 s27, v254, 38
	s_cbranch_vccnz .LBB0_541
	v_and_b32_e32 v83, 64, v243
	v_xor_b32_e32 v82, 16, v243
	v_add_u32_e32 v83, 64, v83
	v_cmp_lt_i32_e32 vcc, v82, v83
	v_xor_b32_e32 v84, 32, v243
	s_nop 0
	v_cndmask_b32_e32 v82, v243, v82, vcc
	v_lshlrev_b32_e32 v82, 2, v82
	ds_bpermute_b32 v82, v82, v96
	v_cmp_lt_i32_e32 vcc, v84, v83
	s_waitcnt lgkmcnt(0)
	v_add_f32_e32 v82, v96, v82
	v_cndmask_b32_e32 v83, v243, v84, vcc
	v_lshlrev_b32_e32 v83, 2, v83
	v_mov_b32_e32 v83, v82
	s_nop 1
	v_permlane32_swap_b32_e32 v83, v82
	s_and_saveexec_b64 s[26:27], s[4:5]
	s_cbranch_execz .LBB0_540
	s_waitcnt lgkmcnt(0)
	v_add_f32_e32 v82, v82, v83
	v_mul_f32_e32 v82, 0x49800000, v82
	v_trunc_f32_e32 v82, v82
	v_mul_f32_e32 v83, 0x2f800000, v82
	v_floor_f32_e32 v83, v83
	v_fmac_f32_e32 v82, 0xcf800000, v83
	v_cvt_u32_f32_e32 v82, v82
	v_cvt_u32_f32_e32 v83, v83
	v_lshl_add_u64 v[84:85], v[168:169], 3, s[16:17]
	global_atomic_add_x2 v[84:85], v[82:83], off offset:256

;     __device__ __forceinline__ void operator()(const f32x4 (&acc)[2][2][4][2], const Unit& u, int wr, int wc, int fr, int fq) const {
;     ...
;                 if (!out) { s += __shfl_xor(s, 16); s += __shfl_xor(s, 32); if (fq == 0) atomicAdd(ssq_next + row, (unsigned long long)(s * 1048576.0f)); } }
.LBB0_549:
	v_and_b32_e32 v67, 64, v243
	v_xor_b32_e32 v66, 16, v243
	v_add_u32_e32 v67, 64, v67
	v_cmp_lt_i32_e32 vcc, v66, v67
	v_xor_b32_e32 v68, 32, v243
	s_nop 0
	v_cndmask_b32_e32 v66, v243, v66, vcc
	v_lshlrev_b32_e32 v66, 2, v66
	ds_bpermute_b32 v66, v66, v80
	v_cmp_lt_i32_e32 vcc, v68, v67
	s_waitcnt lgkmcnt(0)
	v_add_f32_e32 v66, v80, v66
	v_cndmask_b32_e32 v67, v243, v68, vcc
	v_lshlrev_b32_e32 v67, 2, v67
	v_mov_b32_e32 v67, v66
	s_nop 1
	v_permlane32_swap_b32_e32 v67, v66
	s_and_saveexec_b64 s[26:27], s[4:5]
	s_cbranch_execz .LBB0_551
	s_waitcnt lgkmcnt(0)
	v_add_f32_e32 v66, v66, v67
	v_mul_f32_e32 v66, 0x49800000, v66
	v_trunc_f32_e32 v66, v66
	v_mul_f32_e32 v67, 0x2f800000, v66
	v_floor_f32_e32 v67, v67
	v_fmac_f32_e32 v66, 0xcf800000, v67
	v_cvt_u32_f32_e32 v66, v66
	v_cvt_u32_f32_e32 v67, v67
	v_lshl_add_u64 v[68:69], v[168:169], 3, s[16:17]
	global_atomic_add_x2 v[68:69], v[66:67], off offset:384

;     __device__ __forceinline__ void operator()(const f32x4 (&acc)[2][2][4][2], const Unit& u, int wr, int wc, int fr, int fq) const {
;     ...
;                 if (!out) { s += __shfl_xor(s, 16); s += __shfl_xor(s, 32); if (fq == 0) atomicAdd(ssq_next + row, (unsigned long long)(s * 1048576.0f)); } }
.LBB0_560:
	v_readlane_b32 s26, v254, 37
	s_and_b64 vcc, exec, s[10:11]
	v_readlane_b32 s27, v254, 38
	s_cbranch_vccnz .LBB0_564
	v_and_b32_e32 v51, 64, v243
	v_xor_b32_e32 v50, 16, v243
	v_add_u32_e32 v51, 64, v51
	v_cmp_lt_i32_e32 vcc, v50, v51
	v_xor_b32_e32 v52, 32, v243
	s_nop 0
	v_cndmask_b32_e32 v50, v243, v50, vcc
	v_lshlrev_b32_e32 v50, 2, v50
	ds_bpermute_b32 v50, v50, v106
	v_cmp_lt_i32_e32 vcc, v52, v51
	s_waitcnt lgkmcnt(0)
	v_add_f32_e32 v50, v106, v50
	v_cndmask_b32_e32 v51, v243, v52, vcc
	v_lshlrev_b32_e32 v51, 2, v51
	v_mov_b32_e32 v51, v50
	s_nop 1
	v_permlane32_swap_b32_e32 v51, v50
	s_and_saveexec_b64 s[26:27], s[4:5]
	s_cbranch_execz .LBB0_563
	s_waitcnt lgkmcnt(0)
	v_add_f32_e32 v50, v50, v51
	v_mul_f32_e32 v50, 0x49800000, v50
	v_trunc_f32_e32 v50, v50
	v_mul_f32_e32 v51, 0x2f800000, v50
	v_floor_f32_e32 v51, v51
	v_fmac_f32_e32 v50, 0xcf800000, v51
	v_cvt_u32_f32_e32 v50, v50
	v_cvt_u32_f32_e32 v51, v51
	v_lshl_add_u64 v[52:53], v[168:169], 3, s[16:17]
	global_atomic_add_x2 v[52:53], v[50:51], off offset:1024

;     __device__ __forceinline__ void operator()(const f32x4 (&acc)[2][2][4][2], const Unit& u, int wr, int wc, int fr, int fq) const {
;     ...
;                 if (!out) { s += __shfl_xor(s, 16); s += __shfl_xor(s, 32); if (fq == 0) atomicAdd(ssq_next + row, (unsigned long long)(s * 1048576.0f)); } }
.LBB0_571:
	v_readlane_b32 s26, v254, 37
	s_and_b64 vcc, exec, s[10:11]
	v_readlane_b32 s27, v254, 38
	s_cbranch_vccnz .LBB0_575
	v_and_b32_e32 v35, 64, v243
	v_xor_b32_e32 v34, 16, v243
	v_add_u32_e32 v35, 64, v35
	v_cmp_lt_i32_e32 vcc, v34, v35
	v_xor_b32_e32 v36, 32, v243
	s_nop 0
	v_cndmask_b32_e32 v34, v243, v34, vcc
	v_lshlrev_b32_e32 v34, 2, v34
	ds_bpermute_b32 v34, v34, v48
	v_cmp_lt_i32_e32 vcc, v36, v35
	s_waitcnt lgkmcnt(0)
	v_add_f32_e32 v34, v48, v34
	v_cndmask_b32_e32 v35, v243, v36, vcc
	v_lshlrev_b32_e32 v35, 2, v35
	v_mov_b32_e32 v35, v34
	s_nop 1
	v_permlane32_swap_b32_e32 v35, v34
	s_and_saveexec_b64 s[26:27], s[4:5]
	s_cbranch_execz .LBB0_574
	s_waitcnt lgkmcnt(0)
	v_add_f32_e32 v34, v34, v35
	v_mul_f32_e32 v34, 0x49800000, v34
	v_trunc_f32_e32 v34, v34
	v_mul_f32_e32 v35, 0x2f800000, v34
	v_floor_f32_e32 v35, v35
	v_fmac_f32_e32 v34, 0xcf800000, v35
	v_cvt_u32_f32_e32 v34, v34
	v_cvt_u32_f32_e32 v35, v35
	v_lshl_add_u64 v[36:37], v[168:169], 3, s[16:17]
	global_atomic_add_x2 v[36:37], v[34:35], off offset:1152

;     __device__ __forceinline__ void operator()(const f32x4 (&acc)[2][2][4][2], const Unit& u, int wr, int wc, int fr, int fq) const {
;     ...
;                 if (!out) { s += __shfl_xor(s, 16); s += __shfl_xor(s, 32); if (fq == 0) atomicAdd(ssq_next + row, (unsigned long long)(s * 1048576.0f)); } }
.LBB0_582:
	v_readlane_b32 s26, v254, 37
	s_and_b64 vcc, exec, s[10:11]
	v_readlane_b32 s27, v254, 38
	s_cbranch_vccnz .LBB0_586
	v_and_b32_e32 v19, 64, v243
	v_xor_b32_e32 v18, 16, v243
	v_add_u32_e32 v19, 64, v19
	v_cmp_lt_i32_e32 vcc, v18, v19
	v_xor_b32_e32 v20, 32, v243
	s_nop 0
	v_cndmask_b32_e32 v18, v243, v18, vcc
	v_lshlrev_b32_e32 v18, 2, v18
	ds_bpermute_b32 v18, v18, v32
	v_cmp_lt_i32_e32 vcc, v20, v19
	s_waitcnt lgkmcnt(0)
	v_add_f32_e32 v18, v32, v18
	v_cndmask_b32_e32 v19, v243, v20, vcc
	v_lshlrev_b32_e32 v19, 2, v19
	v_mov_b32_e32 v19, v18
	s_nop 1
	v_permlane32_swap_b32_e32 v19, v18
	s_and_saveexec_b64 s[26:27], s[4:5]
	s_cbranch_execz .LBB0_585
	s_waitcnt lgkmcnt(0)
	v_add_f32_e32 v18, v18, v19
	v_mul_f32_e32 v18, 0x49800000, v18
	v_trunc_f32_e32 v18, v18
	v_mul_f32_e32 v19, 0x2f800000, v18
	v_floor_f32_e32 v19, v19
	v_fmac_f32_e32 v18, 0xcf800000, v19
	v_cvt_u32_f32_e32 v18, v18
	v_cvt_u32_f32_e32 v19, v19
	v_lshl_add_u64 v[20:21], v[168:169], 3, s[16:17]
	global_atomic_add_x2 v[20:21], v[18:19], off offset:1280

;     __device__ __forceinline__ void operator()(const f32x4 (&acc)[2][2][4][2], const Unit& u, int wr, int wc, int fr, int fq) const {
;     ...
;                 if (!out) { s += __shfl_xor(s, 16); s += __shfl_xor(s, 32); if (fq == 0) atomicAdd(ssq_next + row, (unsigned long long)(s * 1048576.0f)); } }
.LBB0_594:
	v_and_b32_e32 v3, 64, v243
	v_xor_b32_e32 v2, 16, v243
	v_add_u32_e32 v3, 64, v3
	v_cmp_lt_i32_e32 vcc, v2, v3
	v_xor_b32_e32 v4, 32, v243
	s_nop 0
	v_cndmask_b32_e32 v2, v243, v2, vcc
	v_lshlrev_b32_e32 v2, 2, v2
	ds_bpermute_b32 v2, v2, v16
	v_cmp_lt_i32_e32 vcc, v4, v3
	s_waitcnt lgkmcnt(0)
	v_add_f32_e32 v2, v16, v2
	v_cndmask_b32_e32 v3, v243, v4, vcc
	v_lshlrev_b32_e32 v3, 2, v3
	v_mov_b32_e32 v3, v2
	s_nop 1
	v_permlane32_swap_b32_e32 v3, v2
	s_and_saveexec_b64 s[8:9], s[4:5]
	s_cbranch_execz .LBB0_596
	s_waitcnt lgkmcnt(0)
	v_add_f32_e32 v2, v2, v3
	v_mul_f32_e32 v2, 0x49800000, v2
	v_trunc_f32_e32 v2, v2
	v_mul_f32_e32 v3, 0x2f800000, v2
	v_floor_f32_e32 v3, v3
	v_fmac_f32_e32 v2, 0xcf800000, v3
	v_cvt_u32_f32_e32 v2, v2
	v_cvt_u32_f32_e32 v3, v3
	v_lshl_add_u64 v[4:5], v[168:169], 3, s[16:17]
	global_atomic_add_x2 v[4:5], v[2:3], off offset:1408
